# conv item: next-row prefetch (double buffered); FoX prologue: 8 forget-logit loads batched
# speedup vs baseline: 1.0455x; 1.0065x over previous
; #define LAS __attribute__((address_space(3)))
;     if (s == NSTEP - 1) { step_final(p); return; }
;     const int l = s / (NGRP * NK), g = (s / NK) % NGRP, k = s % NK;
;     if (k == 0) { if (g == 0) step_prep(p, l, lds); step_norm(p, l, g); }
;     else if (k == 1) { pg8::Gemm gm{p.hbuf, p.Wt, MG, NP, DM, 1 << 20, 0}; pg8::StaticOrder S; S.init(MG, NP, gridDim.x, blockIdx.x); EpiG1 E{p.proj, p.vT, p.kiP, p.gq}; pg8::gemm_phase(lds, gm, S, E); }
;     else if (k == 2) { step_mix(p, l, p.ctr + (l * NGRP + g) + 16 * rep, lds, rep ? REPT : 15, rep ? REPS : 63); }
;     else if (k == 3) { pg8::Gemm gm{p.ybuf, p.Wb, MG, 4096, 512, 4, (size_t)MG * 512 * 2}; pg8::BranchOrder S{(int)gridDim.x, (int)blockIdx.x, (MG / 256) * 4}; EpiG2 E{p.gq, p.hbuf}; pg8::gemm_phase(lds, gm, S, E); }
;     else { pg8::Gemm gm{p.hbuf, p.Wo, MG, DM, DM, 1 << 20, 0}; pg8::StaticOrder S; S.init(MG, DM, gridDim.x, blockIdx.x); EpiG3 E{(l == 0) ? p.x : p.out, rep ? (float*)p.proj - (size_t)g * MG * DM : p.out, g * MG}; pg8::gemm_phase(lds, gm, S, E); }
; }
; __global__ __launch_bounds__(512, 2) void mega(Params p, int s0, int s1) {
;     extern __shared__ __attribute__((aligned(16))) unsigned char shm[];
;     LAS unsigned char* lds = (LAS unsigned char*)shm;
;     cg::grid_group grid = cg::this_grid();
;     volatile LAS unsigned* st = (volatile LAS unsigned*)(lds + XB_ST_OFF);
;     if (threadIdx.x == 0) { st[0] = 0u; st[1] = 0u; }
;     __syncthreads();
;     const XcdBarrier xb = xcd_barrier_post(p.bar, st);
;     for (int s = s0; s < s1; ++s) { run_step(p, s, lds);
;         if (s + 1 < s1) { if (s1 < 0) grid.sync(); else xcd_barrier(xb); } }
; }
.LBB0_5:
	s_or_b64 exec, exec, s[2:3]
	s_load_dwordx2 s[2:3], s[0:1], 0xe0
	s_waitcnt lgkmcnt(0)
	v_writelane_b32 v251, s2, 15
	s_nop 1
	v_writelane_b32 v251, s3, 16
	s_cmp_ge_i32 s2, s3
	s_cbranch_scc1 .Lnear_exit
	v_readlane_b32 s26, v251, 0
	s_cmpk_lt_i32 s26, 0x100
	s_cselect_b64 s[2:3], -1, 0
	s_load_dwordx16 s[44:59], s[0:1], 0x0
	s_load_dwordx16 s[4:19], s[0:1], 0x80
	v_writelane_b32 v251, s2, 17
	s_and_b32 s22, s26, 7
	s_lshl_b32 s22, s22, 5
	s_lshr_b32 s21, s26, 3
	s_add_i32 s21, s22, s21
	s_ashr_i32 s22, s21, 2
	s_and_b32 s21, s21, 3
	v_writelane_b32 v251, s3, 18
	s_mov_b32 s2, s22
	v_writelane_b32 v251, s2, 19
	s_ashr_i32 s23, s22, 31
	s_load_dwordx2 s[28:29], s[0:1], 0xe8
	v_writelane_b32 v251, s3, 20
	s_lshl_b64 s[2:3], s[22:23], 18
	v_writelane_b32 v251, s21, 21
	s_lshl_b32 s21, s21, 18
	s_waitcnt lgkmcnt(0)
	s_add_u32 s22, s6, s21
	s_addc_u32 s23, s7, 0
	s_add_u32 s2, s16, s2
	s_addc_u32 s3, s17, s3
	s_add_u32 s24, s22, 0x20000
	s_addc_u32 s25, s23, 0
	v_writelane_b32 v251, s24, 22
	s_load_dwordx8 s[36:43], s[0:1], 0xc0
	v_lshrrev_b32_e32 v1, 20, v0
	v_writelane_b32 v251, s25, 23
	s_add_u32 s24, s2, 0x20000
	v_writelane_b32 v251, s2, 24
	s_addc_u32 s25, s3, 0
	v_lshrrev_b32_e32 v0, 10, v0
	v_writelane_b32 v251, s3, 25
	v_writelane_b32 v251, s24, 26
	s_add_u32 s2, s22, 0x20080
	v_or_b32_e32 v0, v0, v1
	v_writelane_b32 v251, s25, 27
	v_writelane_b32 v251, s22, 28
	s_addc_u32 s3, s23, 0
	s_cmpk_lt_i32 s26, 0xb00
	v_writelane_b32 v251, s23, 29
	v_writelane_b32 v251, s2, 30
	s_movk_i32 s22, 0x161
	s_mov_b64 s[66:67], s[58:59]
	v_writelane_b32 v251, s3, 31
	s_cselect_b64 s[2:3], -1, 0
	v_writelane_b32 v251, s2, 32
	s_mov_b64 s[64:65], s[56:57]
	v_mbcnt_lo_u32_b32 v205, -1, 0
	v_writelane_b32 v251, s3, 33
	s_ashr_i32 s2, s26, 31
	v_writelane_b32 v251, s2, 34
	s_lshr_b32 s2, s2, 29
	s_add_i32 s2, s26, s2
	s_ashr_i32 s3, s2, 3
	s_and_b32 s2, s2, -8
	s_sub_i32 s2, s26, s2
	s_lshl_b32 s21, s2, 5
	s_cmp_lt_i32 s2, 0
	s_cselect_b32 s22, s22, 0x160
	s_mul_i32 s22, s22, s2
	s_mul_i32 s23, s2, 33
	s_cselect_b32 s24, s23, s21
	s_add_i32 s22, s22, s3
	s_mul_hi_i32 s21, s22, 0x2e8ba2e9
	s_lshr_b32 s23, s21, 31
	s_ashr_i32 s21, s21, 5
	s_add_i32 s21, s21, s23
	s_mul_i32 s23, s21, 0xb0
	s_sub_i32 s22, s22, s23
	s_bfe_u32 s23, s22, 0x2001d
	s_add_i32 s23, s22, s23
	s_sext_i32_i16 s25, s23
	s_and_b32 s23, s23, 0xfffc
	s_ashr_i32 s25, s25, 2
	s_sub_i32 s22, s22, s23
	s_mul_i32 s2, s2, 5
	s_lshl_b32 s21, s21, 2
	s_sext_i32_i16 s22, s22
	s_add_i32 s2, s2, s25
	s_add_i32 s30, s21, s22
	s_bfe_i32 s21, s2, 0x80000
	s_mul_i32 s21, s21, 47
	s_sext_i32_i16 s22, s21
	s_ashr_i32 s22, s22, 11
	s_bfe_u32 s21, s21, 0x1000f
	s_add_i32 s21, s22, s21
	s_mul_i32 s21, s21, 44
	s_sub_i32 s2, s2, s21
	s_ashr_i32 s21, s28, 31
	s_cmpk_lt_i32 s26, 0xf10
	v_writelane_b32 v251, s21, 35
	s_cselect_b64 s[22:23], -1, 0
	v_writelane_b32 v251, s22, 36
	s_cmp_lg_u64 s[58:59], 0
	v_mov_b32_e32 v1, 0
	v_writelane_b32 v251, s23, 37
	s_cselect_b64 s[22:23], -1, 0
	v_writelane_b32 v251, s22, 38
	s_lshl_b32 s21, s26, 3
	s_lshl_b32 s82, s28, 3
	v_writelane_b32 v251, s23, 39
	s_load_dwordx2 s[22:23], s[0:1], 0xe0
	v_writelane_b32 v251, s21, 40
	v_mov_b32_e32 v199, 0x358637bd
	v_mov_b32_e32 v200, 0x10001
	v_mov_b32_e32 v201, 0x3ecc95a3
	s_waitcnt lgkmcnt(0)
	s_cmp_gt_i32 s23, -1
	s_cselect_b64 s[22:23], -1, 0
	v_writelane_b32 v251, s22, 41
	v_mov_b32_e32 v202, 1
	v_mov_b32_e32 v203, 0x3b808081
	v_writelane_b32 v251, s23, 42
	s_add_u32 s22, s40, 0x200
	s_addc_u32 s23, s41, 0
	v_writelane_b32 v251, s22, 43
	v_mov_b32_e32 v204, 0xa00
	v_mbcnt_hi_u32_b32 v206, -1, v205
	v_writelane_b32 v251, s23, 44
	s_add_u32 s22, s40, 0x1000
	s_addc_u32 s23, s41, 0
	v_writelane_b32 v251, s22, 45
	v_mov_b32_e32 v207, 0xfff0fff
	v_mov_b32_e32 v208, 0xff800000
	v_writelane_b32 v251, s23, 46
	s_add_u32 s22, s40, 0x1100
	s_addc_u32 s23, s41, 0
	v_writelane_b32 v251, s22, 47
	v_mov_b32_e32 v162, 0x3f317218
	v_mov_b32_e32 v209, 0x7f800000
	v_writelane_b32 v251, s23, 48
	s_add_u32 s22, s40, 0x1200
	s_addc_u32 s23, s41, 0
	v_writelane_b32 v251, s22, 49
	v_mov_b32_e32 v210, 0x7fc00000
	v_mov_b64_e32 v[164:165], 0xaff
	v_writelane_b32 v251, s23, 50
	s_add_u32 s22, s40, 0x1300
	s_addc_u32 s23, s41, 0
	v_writelane_b32 v251, s22, 51
	s_cmp_eq_u32 s20, 15
	v_mov_b64_e32 v[166:167], 0xb00
	v_writelane_b32 v251, s23, 52
	s_cselect_b64 s[22:23], -1, 0
	v_writelane_b32 v251, s22, 53
	s_cmp_eq_u32 s20, 14
	v_mov_b64_e32 v[168:169], 0xff
	v_writelane_b32 v251, s23, 54
	s_cselect_b64 s[22:23], -1, 0
	v_writelane_b32 v251, s22, 55
	s_cmp_eq_u32 s20, 13
	v_mov_b64_e32 v[170:171], 0x100
	v_writelane_b32 v251, s23, 56
	s_cselect_b64 s[22:23], -1, 0
	v_writelane_b32 v251, s22, 57
	s_cmp_eq_u32 s20, 12
	s_movk_i32 s84, 0x2000
	v_writelane_b32 v251, s23, 58
	s_cselect_b64 s[22:23], -1, 0
	v_writelane_b32 v251, s22, 59
	s_cmp_eq_u32 s20, 11
	s_movk_i32 s33, 0x5800
	v_writelane_b32 v251, s23, 60
	s_cselect_b64 s[22:23], -1, 0
	v_writelane_b32 v251, s22, 61
	s_cmp_eq_u32 s20, 10
	s_mov_b32 s85, 0x800000
	v_writelane_b32 v251, s23, 62
	s_cselect_b64 s[22:23], -1, 0
	v_writelane_b32 v251, s22, 63
	s_cmp_eq_u32 s20, 9
	s_mov_b32 s86, 0xd000
	v_writelane_b32 v252, s23, 0
	s_cselect_b64 s[22:23], -1, 0
	v_writelane_b32 v252, s22, 1
	s_cmp_eq_u32 s20, 8
	s_movk_i32 s87, 0x204
	v_writelane_b32 v252, s23, 2
	s_cselect_b64 s[22:23], -1, 0
	v_writelane_b32 v252, s22, 3
	s_cmp_eq_u32 s20, 7
	s_mov_b64 s[90:91], 0x800
	v_writelane_b32 v252, s23, 4
	s_cselect_b64 s[22:23], -1, 0
	v_writelane_b32 v252, s22, 5
	s_cmp_eq_u32 s20, 6
	s_nop 0
	v_writelane_b32 v252, s23, 6
	s_cselect_b64 s[22:23], -1, 0
	v_writelane_b32 v252, s22, 7
	s_cmp_eq_u32 s20, 5
; #define LAS __attribute__((address_space(3)))
;     if (s == NSTEP - 1) { step_final(p); return; }
;     const int l = s / (NGRP * NK), g = (s / NK) % NGRP, k = s % NK;
;     if (k == 0) { if (g == 0) step_prep(p, l, lds); step_norm(p, l, g); }
;     else if (k == 1) { pg8::Gemm gm{p.hbuf, p.Wt, MG, NP, DM, 1 << 20, 0}; pg8::StaticOrder S; S.init(MG, NP, gridDim.x, blockIdx.x); EpiG1 E{p.proj, p.vT, p.kiP, p.gq}; pg8::gemm_phase(lds, gm, S, E); }
;     else if (k == 2) { step_mix(p, l, p.ctr + (l * NGRP + g) + 16 * rep, lds, rep ? REPT : 15, rep ? REPS : 63); }
;     else if (k == 3) { pg8::Gemm gm{p.ybuf, p.Wb, MG, 4096, 512, 4, (size_t)MG * 512 * 2}; pg8::BranchOrder S{(int)gridDim.x, (int)blockIdx.x, (MG / 256) * 4}; EpiG2 E{p.gq, p.hbuf}; pg8::gemm_phase(lds, gm, S, E); }
;     else { pg8::Gemm gm{p.hbuf, p.Wo, MG, DM, DM, 1 << 20, 0}; pg8::StaticOrder S; S.init(MG, DM, gridDim.x, blockIdx.x); EpiG3 E{(l == 0) ? p.x : p.out, rep ? (float*)p.proj - (size_t)g * MG * DM : p.out, g * MG}; pg8::gemm_phase(lds, gm, S, E); }
; }
; __global__ __launch_bounds__(512, 2) void mega(Params p, int s0, int s1) {
;     extern __shared__ __attribute__((aligned(16))) unsigned char shm[];
;     LAS unsigned char* lds = (LAS unsigned char*)shm;
;     cg::grid_group grid = cg::this_grid();
;     volatile LAS unsigned* st = (volatile LAS unsigned*)(lds + XB_ST_OFF);
;     if (threadIdx.x == 0) { st[0] = 0u; st[1] = 0u; }
;     __syncthreads();
;     const XcdBarrier xb = xcd_barrier_post(p.bar, st);
;     for (int s = s0; s < s1; ++s) { run_step(p, s, lds);
;         if (s + 1 < s1) { if (s1 < 0) grid.sync(); else xcd_barrier(xb); } }
; }
	s_nop 0
	v_writelane_b32 v252, s23, 8
	s_cselect_b64 s[22:23], -1, 0
	v_writelane_b32 v252, s22, 9
	s_cmp_eq_u32 s20, 4
	s_nop 0
	v_writelane_b32 v252, s23, 10
	s_cselect_b64 s[22:23], -1, 0
	v_writelane_b32 v252, s22, 11
	s_cmp_eq_u32 s20, 3
	s_nop 0
	v_writelane_b32 v252, s23, 12
	s_cselect_b64 s[22:23], -1, 0
	v_writelane_b32 v252, s22, 13
	s_cmp_eq_u32 s20, 2
	s_nop 0
	v_writelane_b32 v252, s23, 14
	s_cselect_b64 s[22:23], -1, 0
	v_writelane_b32 v252, s22, 15
	s_cmp_eq_u32 s20, 1
	s_nop 0
	v_writelane_b32 v252, s23, 16
	s_cselect_b64 s[22:23], -1, 0
	v_writelane_b32 v252, s22, 17
	s_cmp_eq_u32 s20, 0
	s_nop 0
	v_writelane_b32 v252, s23, 18
	s_cselect_b64 s[22:23], -1, 0
	s_lshl_b32 s20, s20, 8
	s_add_u32 s20, s40, s20
	v_writelane_b32 v252, s22, 19
	s_addc_u32 s21, s41, 0
	s_nop 0
	v_writelane_b32 v252, s23, 20
	s_add_u32 s22, s20, 0x1400
	s_addc_u32 s23, s21, 0
	v_writelane_b32 v252, s22, 21
	s_add_u32 s20, s20, 0x2400
	s_addc_u32 s21, s21, 0
	v_writelane_b32 v252, s23, 22
	v_writelane_b32 v252, s20, 23
	s_mov_b32 s22, s30
	s_nop 0
	v_writelane_b32 v252, s21, 24
	s_add_u32 s20, s40, 0x3400
	s_addc_u32 s21, s41, 0
	v_writelane_b32 v252, s20, 25
	s_nop 1
	v_writelane_b32 v252, s21, 26
	s_add_u32 s20, s40, 0x3500
	s_addc_u32 s21, s41, 0
	v_writelane_b32 v252, s20, 27
	s_ashr_i32 s31, s30, 31
	s_nop 0
	v_writelane_b32 v252, s21, 28
	s_bfe_i64 s[20:21], s[2:3], 0x80000
	v_writelane_b32 v252, s22, 29
	s_lshl_b64 s[20:21], s[20:21], 19
	s_sext_i32_i8 s2, s2
	v_writelane_b32 v252, s23, 30
	s_lshl_b64 s[22:23], s[30:31], 19
	s_add_u32 s20, s4, s20
	s_addc_u32 s21, s5, s21
	s_add_u32 s22, s12, s22
	s_addc_u32 s23, s13, s23
	s_add_u32 s30, s20, 0x40000
	s_addc_u32 s31, s21, 0
	v_writelane_b32 v252, s30, 31
	s_nop 1
	v_writelane_b32 v252, s31, 32
	s_add_u32 s30, s22, 0x40000
	v_writelane_b32 v252, s22, 33
	s_addc_u32 s31, s23, 0
	s_nop 0
	v_writelane_b32 v252, s23, 34
	v_writelane_b32 v252, s30, 35
	s_add_u32 s22, s20, 0x40080
	s_nop 0
	v_writelane_b32 v252, s31, 36
	v_writelane_b32 v252, s20, 37
	s_addc_u32 s23, s21, 0
	s_add_i32 s3, s24, s3
	v_writelane_b32 v252, s21, 38
	s_ashr_i32 s20, s3, 31
	s_lshr_b32 s20, s20, 28
	s_add_i32 s20, s3, s20
	s_and_b32 s21, s20, 0xfff0
	s_sub_i32 s3, s3, s21
	s_bfe_i32 s21, s3, 0x80000
	s_bfe_u32 s21, s21, 0x2000d
	v_writelane_b32 v252, s22, 39
	s_add_i32 s21, s3, s21
	s_ashr_i32 s20, s20, 4
	v_writelane_b32 v252, s23, 40
	s_and_b32 s22, s21, 0xfc
	s_sub_i32 s3, s3, s22
	s_bfe_i32 s21, s21, 0x80000
	s_lshl_b32 s20, s20, 2
	s_sext_i32_i16 s21, s21
	s_sext_i32_i8 s3, s3
	s_add_i32 s24, s20, s3
	s_ashr_i32 s3, s21, 2
	v_writelane_b32 v252, s3, 41
	s_lshr_b32 s20, s21, 2
	s_mov_b32 s22, s24
	s_load_dword s3, s[0:1], 0xf0
	s_ashr_i32 s25, s24, 31
	s_bfe_i64 s[20:21], s[20:21], 0x100000
	v_writelane_b32 v252, s22, 42
	s_lshl_b64 s[20:21], s[20:21], 19
	s_mov_b32 s31, 0
	v_writelane_b32 v252, s23, 43
	s_lshl_b64 s[22:23], s[24:25], 19
	s_add_u32 s20, s8, s20
	s_addc_u32 s21, s9, s21
	v_writelane_b32 v252, s2, 44
	s_mul_i32 s2, s29, s28
	s_add_u32 s22, s12, s22
	s_waitcnt lgkmcnt(0)
	s_mul_i32 s2, s2, s3
	s_addc_u32 s23, s13, s23
	v_writelane_b32 v252, s2, 45
	s_movk_i32 s2, 0x3ff
	v_and_or_b32 v0, v0, s2, v198
	s_add_u32 s2, s20, 0x40000
	s_addc_u32 s3, s21, 0
	v_writelane_b32 v252, s2, 46
	s_nop 1
	v_writelane_b32 v252, s3, 47
	s_add_u32 s2, s22, 0x40000
	v_writelane_b32 v252, s22, 48
	s_addc_u32 s3, s23, 0
	s_nop 0
	v_writelane_b32 v252, s23, 49
	v_writelane_b32 v252, s2, 50
	s_nop 1
	v_writelane_b32 v252, s3, 51
	s_add_u32 s2, s20, 0x40080
	v_writelane_b32 v252, s20, 52
	s_addc_u32 s3, s21, 0
	s_nop 0
	v_writelane_b32 v252, s21, 53
	v_writelane_b32 v252, s2, 54
	s_nop 1
	v_writelane_b32 v252, s3, 55
	s_add_u32 s2, s54, 64
	s_addc_u32 s3, s55, 0
	v_writelane_b32 v252, s2, 56
	s_mov_b64 s[60:61], s[52:53]
	s_mov_b64 s[58:59], s[50:51]
	v_writelane_b32 v252, s3, 57
	s_add_u32 s2, s48, 0x1810
	v_writelane_b32 v252, s2, 58
	s_addc_u32 s2, s49, 0
	v_writelane_b32 v252, s2, 59
	s_lshl_b32 s2, s26, 2
	v_writelane_b32 v252, s2, 60
	s_lshl_b32 s2, s28, 2
	v_writelane_b32 v252, s2, 61
	s_add_u32 s2, s48, 0xc730
	v_writelane_b32 v252, s2, 62
	s_addc_u32 s2, s49, 0
	v_writelane_b32 v252, s2, 63
	s_add_u32 s2, s48, 0x17650
	v_writelane_b32 v253, s2, 0
	s_addc_u32 s2, s49, 0
	v_writelane_b32 v253, s2, 1
	s_add_u32 s2, s48, 0x22570
	v_writelane_b32 v253, s2, 2
	s_mov_b64 s[56:57], s[48:49]
	s_mov_b64 s[54:55], s[46:47]
	s_mov_b64 s[52:53], s[44:45]
	v_writelane_b32 v253, s52, 3
	s_addc_u32 s2, s49, 0
	s_load_dwordx16 s[36:51], s[0:1], 0x40
	v_writelane_b32 v253, s53, 4
	v_writelane_b32 v253, s54, 5
	v_writelane_b32 v253, s55, 6
	v_writelane_b32 v253, s56, 7
	v_writelane_b32 v253, s57, 8
	v_writelane_b32 v253, s58, 9
	v_writelane_b32 v253, s59, 10
	v_writelane_b32 v253, s60, 11
	v_writelane_b32 v253, s61, 12
	v_writelane_b32 v253, s62, 13
	v_writelane_b32 v253, s63, 14
	v_writelane_b32 v253, s64, 15
	v_writelane_b32 v253, s65, 16
	v_writelane_b32 v253, s66, 17
	v_writelane_b32 v253, s67, 18
	v_writelane_b32 v253, s2, 19
	s_add_u32 s2, s12, 0x400
	s_addc_u32 s3, s13, 0
	v_writelane_b32 v253, s2, 20
	s_waitcnt lgkmcnt(0)
	s_add_u32 s0, s50, 0xc00
	v_writelane_b32 v253, s3, 21
	v_writelane_b32 v253, s36, 22
	s_addc_u32 s1, s51, 0
	s_ashr_i32 s83, s82, 31
	v_writelane_b32 v253, s37, 23
	v_writelane_b32 v253, s38, 24
	v_writelane_b32 v253, s39, 25
	v_writelane_b32 v253, s40, 26
	v_writelane_b32 v253, s41, 27
	v_writelane_b32 v253, s42, 28
	v_writelane_b32 v253, s43, 29
	v_writelane_b32 v253, s44, 30
	v_writelane_b32 v253, s45, 31
	v_writelane_b32 v253, s46, 32
	v_writelane_b32 v253, s47, 33
	v_writelane_b32 v253, s48, 34
	v_writelane_b32 v253, s49, 35
	v_writelane_b32 v253, s50, 36
	v_writelane_b32 v253, s51, 37
	v_writelane_b32 v253, s0, 38
	s_lshl_b64 s[88:89], s[82:83], 12
	s_mov_b64 s[2:3], 0x80
	v_writelane_b32 v253, s1, 39
	s_add_i32 s0, 0, 0x202c0
	v_writelane_b32 v253, s0, 40
	s_add_i32 s0, 0, 0x24000
	v_writelane_b32 v253, s0, 41
	s_add_i32 s0, 0, 0x24004
	v_writelane_b32 v253, s0, 42
	v_cmp_eq_u32_e64 s[0:1], 0, v0
	s_mov_b32 s36, 0x3e0293ee
	s_nop 0
	v_writelane_b32 v253, s0, 43
	s_nop 1
	v_writelane_b32 v253, s1, 44
	s_mov_b32 s0, s82
	v_writelane_b32 v253, s0, 45
	s_nop 1
	v_writelane_b32 v253, s1, 46
	v_writelane_b32 v253, s88, 47
	s_nop 1
	v_writelane_b32 v253, s89, 48
	s_branch .LBB0_11
.Lnear_exit:
	s_endpgm
.LBB0_7:
	buffer_inv sc1

; __device__ __forceinline__ float bflo(unsigned w) { return __uint_as_float(w << 16); }
; __device__ __forceinline__ float bfhi(unsigned w) { return __uint_as_float(w & 0xffff0000u); }
; __device__ __forceinline__ int opq(int x) { asm volatile("" : "+v"(x)); return x; }
; __device__ __forceinline__ void item_conv(const Params& p, int l, int it) {
;     const int tid = opq(threadIdx.x), cc = tid & 63, tb = tid >> 6; const int r0 = it * 128 + tb * 16, s0 = r0 & 4095;
;     float w0[8], w1[8], w2[8];
; #pragma unroll
;     for (int e = 0; e < 8; ++e) { w0[e] = p.conv_w[(l * 3 + 0) * 512 + cc * 8 + e]; w1[e] = p.conv_w[(l * 3 + 1) * 512 + cc * 8 + e]; w2[e] = p.conv_w[(l * 3 + 2) * 512 + cc * 8 + e]; }
;     float y2[8], y1[8];
;     auto ld8 = [&](int r, int col, float* o) { const u32x4 w = *(const u32x4*)(p.proj + (size_t)r * NP + col + cc * 8);
; #pragma unroll
;         for (int e = 0; e < 4; ++e) { o[2 * e] = bflo(w[e]); o[2 * e + 1] = bfhi(w[e]); } };
;     auto ycx = [&](int r, float* o) { float a[8], b[8]; ld8(r, C_CC, a); ld8(r, C_CX, b);
; #pragma unroll
;         for (int e = 0; e < 8; ++e) o[e] = a[e] * b[e]; };
; #pragma unroll
;     for (int e = 0; e < 8; ++e) { y2[e] = 0.f; y1[e] = 0.f; }
;     if (s0 >= 2) ycx(r0 - 2, y2);
;     if (s0 >= 1) ycx(r0 - 1, y1);
;     for (int i = 0; i < 16; ++i) {
.LBB0_153:
	s_andn2_saveexec_b64 s[0:1], s[0:1]
	v_mov_b32_e32 v0, v1
	v_mov_b64_e32 v[40:41], v[0:1]
	v_mov_b64_e32 v[38:39], v[0:1]
	v_mov_b64_e32 v[36:37], v[0:1]
	v_mov_b64_e32 v[34:35], v[0:1]
	v_mov_b64_e32 v[46:47], v[0:1]
	v_mov_b64_e32 v[48:49], v[0:1]
	v_mov_b64_e32 v[58:59], v[0:1]
	v_mov_b64_e32 v[60:61], v[0:1]
	s_or_b64 exec, exec, s[0:1]
	s_add_i32 s0, s20, 0xfffbc000
	v_add_u32_e32 v28, s0, v28
	v_ashrrev_i32_e32 v29, 31, v28
	v_lshlrev_b64 v[28:29], 10, v[28:29]
	v_lshl_add_u64 v[42:43], s[16:17], 0, v[28:29]
	v_mov_b64_e32 v[28:29], s[14:15]
	s_waitcnt vmcnt(0)
	v_mov_b32_e32 v0, v7
	v_mov_b32_e32 v7, v9
	v_mov_b32_e32 v9, v3
	v_mov_b32_e32 v3, v5
	v_mad_i64_i32 v[44:45], s[0:1], v27, s33, v[28:29]
	s_waitcnt vmcnt(1)
	v_swap_b32 v5, v20
	v_mov_b32_e32 v3, v18
	v_mov_b32_e32 v18, v9
	s_waitcnt vmcnt(0)
	v_mov_b32_e32 v9, v24
	v_mov_b32_e32 v24, v7
	v_mov_b32_e32 v7, v22
	v_mov_b32_e32 v22, v0
	v_lshlrev_b32_e32 v0, 1, v26
	s_mov_b32 s0, 16
	v_lshl_add_u64 v[98:99], v[44:45], 0, v[0:1]
	v_add_co_u32_e32 v100, vcc, 0x1000, v98
	s_nop 1
	v_addc_co_u32_e32 v101, vcc, 0, v99, vcc
	v_add_co_u32_e32 v102, vcc, s84, v98
	s_nop 1
	v_addc_co_u32_e32 v103, vcc, 0, v99, vcc
	global_load_dwordx4 v[66:69], v[100:101], off offset:3072
	global_load_dwordx4 v[70:73], v[102:103], off
	global_load_dwordx4 v[74:77], v[100:101], off offset:2048
	global_load_dwordx4 v[78:81], v[102:103], off offset:1024
.Lconv_X:
	s_mov_b64 s[22:23], 0x5800
	v_lshl_add_u64 v[100:101], v[100:101], 0, s[22:23]
	v_lshl_add_u64 v[102:103], v[102:103], 0, s[22:23]
	s_cmp_eq_u32 s0, 1
	s_cbranch_scc1 .Lconv_np_X
	global_load_dwordx4 v[82:85], v[100:101], off offset:3072
	global_load_dwordx4 v[86:89], v[102:103], off
	global_load_dwordx4 v[90:93], v[100:101], off offset:2048
	global_load_dwordx4 v[94:97], v[102:103], off offset:1024
	s_waitcnt vmcnt(4)
	s_branch .Lconv_go_X

; __device__ __forceinline__ unsigned cvtpk(float lo, float hi) { unsigned r; asm volatile("v_cvt_pk_bf16_f32 %0, %1, %2" : "=v"(r) : "v"(lo), "v"(hi)); return r; }
; __device__ __forceinline__ float siluf_(float x) { return x * sigmoidf_(x); }
; __device__ __forceinline__ void item_conv(const Params& p, int l, int it) {
;     ...
;     for (int i = 0; i < 16; ++i) {
;         const int r = r0 + i; float y0[8], bb[8], zz[8], o[8]; ycx(r, y0); ld8(r, C_CB, bb); ld8(r, C_CZ, zz);
; #pragma unroll
;         for (int e = 0; e < 8; ++e) { o[e] = bb[e] * (w0[e] * y2[e] + w1[e] * y1[e] + w2[e] * y0[e]) * siluf_(zz[e]); y2[e] = y1[e]; y1[e] = y0[e]; }
;         u32x4 ow = {cvtpk(o[0], o[1]), cvtpk(o[2], o[3]), cvtpk(o[4], o[5]), cvtpk(o[6], o[7])};
;         *(u32x4*)(p.ybuf + ((size_t)2 * MG + r) * 512 + cc * 8) = ow;
;     }
.Lconv_go_X:
	v_lshl_add_u64 v[30:31], v[44:45], 0, v[0:1]
	v_add_co_u32_e32 v62, vcc, 0x1000, v30
	v_mov_b64_e32 v[50:51], v[34:35]
	s_nop 0
	v_addc_co_u32_e32 v63, vcc, 0, v31, vcc
	v_add_co_u32_e32 v64, vcc, s84, v30
	v_mov_b32_e32 v26, v66
	v_mov_b32_e32 v27, v67
	v_mov_b32_e32 v28, v68
	v_mov_b32_e32 v29, v69
	s_nop 0
	v_addc_co_u32_e32 v65, vcc, 0, v31, vcc
	v_mov_b32_e32 v30, v70
	v_mov_b32_e32 v31, v71
	v_mov_b32_e32 v32, v72
	v_mov_b32_e32 v33, v73
	v_mov_b64_e32 v[52:53], v[36:37]
	v_mov_b64_e32 v[54:55], v[38:39]
	v_mov_b64_e32 v[56:57], v[40:41]
	s_mov_b64 s[22:23], 0x400
	s_add_i32 s0, s0, -1
	s_cmp_eq_u32 s0, 0
	v_and_b32_e32 v34, 0xffff0000, v26
	v_lshlrev_b32_e32 v35, 16, v26
	v_and_b32_e32 v26, 0xffff0000, v27
	v_and_b32_e32 v36, 0xffff0000, v30
	v_lshlrev_b32_e32 v37, 16, v30
	v_lshlrev_b32_e32 v27, 16, v27
	v_and_b32_e32 v30, 0xffff0000, v31
	v_lshlrev_b32_e32 v31, 16, v31
	v_pk_mul_f32 v[34:35], v[34:35], v[36:37]
	v_pk_mul_f32 v[36:37], v[26:27], v[30:31]
	v_and_b32_e32 v26, 0xffff0000, v28
	v_lshlrev_b32_e32 v27, 16, v28
	v_and_b32_e32 v30, 0xffff0000, v32
	v_lshlrev_b32_e32 v31, 16, v32
	v_pk_mul_f32 v[38:39], v[26:27], v[30:31]
	v_and_b32_e32 v26, 0xffff0000, v29
	v_lshlrev_b32_e32 v27, 16, v29
	v_and_b32_e32 v28, 0xffff0000, v33
	v_lshlrev_b32_e32 v29, 16, v33
	v_pk_mul_f32 v[40:41], v[26:27], v[28:29]
	v_mov_b32_e32 v26, v74
	v_mov_b32_e32 v27, v75
	v_mov_b32_e32 v28, v76
	v_mov_b32_e32 v29, v77
	v_mov_b32_e32 v30, v78
	v_mov_b32_e32 v31, v79
	v_mov_b32_e32 v32, v80
	v_mov_b32_e32 v33, v81
	v_mov_b32_e32 v62, v61
	v_mov_b32_e32 v63, v35
	v_pk_mul_f32 v[62:63], v[6:7], v[62:63]
	v_lshlrev_b32_e32 v64, 16, v26
	v_fma_f32 v61, v14, v51, v62
	v_lshlrev_b32_e32 v65, 16, v30
	v_add_f32_e32 v62, v61, v63
	v_mul_f32_e32 v61, 0xbfb8aa3b, v65
	v_exp_f32_e32 v61, v61
	s_nop 0
	v_add_f32_e32 v61, 1.0, v61
	v_rcp_f32_e32 v63, v61
	v_mov_b32_e32 v61, v34
	v_pk_mul_f32 v[60:61], v[22:23], v[60:61]
	v_pk_mul_f32 v[62:63], v[62:63], v[64:65]
	s_nop 0
	v_mul_f32_e32 v64, v62, v63
	v_and_b32_e32 v63, 0xffff0000, v30
	v_and_b32_e32 v62, 0xffff0000, v26
	v_mul_f32_e32 v26, 0xbfb8aa3b, v63
	v_exp_f32_e32 v26, v26
	v_fma_f32 v60, v15, v50, v60
	v_add_f32_e32 v60, v60, v61
	v_and_b32_e32 v30, 0xffff0000, v27
	v_add_f32_e32 v26, 1.0, v26
	v_rcp_f32_e32 v61, v26
	s_nop 0
	v_pk_mul_f32 v[60:61], v[60:61], v[62:63]
	s_nop 0
	v_mul_f32_e32 v65, v60, v61
	v_mov_b32_e32 v60, v59
	v_mov_b32_e32 v61, v37
	v_lshlrev_b32_e32 v63, 16, v31
	v_and_b32_e32 v31, 0xffff0000, v31
	v_pk_mul_f32 v[60:61], v[8:9], v[60:61]
	v_lshlrev_b32_e32 v62, 16, v27
	v_mul_f32_e32 v27, 0xbfb8aa3b, v31
	v_fma_f32 v26, v16, v53, v60
	v_exp_f32_e32 v27, v27
	v_add_f32_e32 v60, v26, v61
	v_mul_f32_e32 v26, 0xbfb8aa3b, v63
	v_exp_f32_e32 v26, v26
	v_add_f32_e32 v27, 1.0, v27
	v_mov_b32_e32 v59, v36
	v_rcp_f32_e32 v27, v27
	v_add_f32_e32 v26, 1.0, v26
	v_pk_mul_f32 v[58:59], v[24:25], v[58:59]
	v_rcp_f32_e32 v61, v26
	v_fma_f32 v26, v17, v52, v58
	v_add_f32_e32 v26, v26, v59
	v_pk_mul_f32 v[26:27], v[26:27], v[30:31]
	v_lshlrev_b32_e32 v31, 16, v32
	v_mul_f32_e32 v58, v26, v27
	v_mov_b32_e32 v26, v49
	v_mov_b32_e32 v27, v39
	v_pk_mul_f32 v[26:27], v[2:3], v[26:27]
	v_lshlrev_b32_e32 v30, 16, v28
	v_fma_f32 v26, v10, v55, v26
	v_add_f32_e32 v26, v26, v27
	v_mul_f32_e32 v27, 0xbfb8aa3b, v31
	v_exp_f32_e32 v27, v27
	v_mov_b32_e32 v49, v38
	v_pk_mul_f32 v[60:61], v[60:61], v[62:63]
	v_add_f32_e32 v27, 1.0, v27
	v_rcp_f32_e32 v27, v27
	v_mul_f32_e32 v60, v60, v61
	v_pk_mul_f32 v[26:27], v[26:27], v[30:31]
	s_nop 0
	v_mul_f32_e32 v59, v26, v27
	v_pk_mul_f32 v[26:27], v[18:19], v[48:49]
	v_and_b32_e32 v31, 0xffff0000, v32
	v_fma_f32 v26, v11, v54, v26
	v_add_f32_e32 v26, v26, v27
	v_mul_f32_e32 v27, 0xbfb8aa3b, v31
	v_exp_f32_e32 v27, v27
	v_and_b32_e32 v30, 0xffff0000, v28
	v_mov_b64_e32 v[48:49], v[54:55]
	v_add_f32_e32 v27, 1.0, v27
	v_rcp_f32_e32 v27, v27
	s_nop 0
	v_pk_mul_f32 v[26:27], v[26:27], v[30:31]
	s_nop 0
	v_mul_f32_e32 v28, v26, v27
	v_mov_b32_e32 v26, v47
	v_mov_b32_e32 v27, v41
	v_pk_mul_f32 v[26:27], v[4:5], v[26:27]
	v_lshlrev_b32_e32 v31, 16, v33
	v_fma_f32 v26, v12, v57, v26
	v_add_f32_e32 v26, v26, v27
	v_mul_f32_e32 v27, 0xbfb8aa3b, v31
	v_exp_f32_e32 v27, v27
	v_lshlrev_b32_e32 v30, 16, v29
	v_mov_b32_e32 v47, v40
	v_add_f32_e32 v27, 1.0, v27
	v_rcp_f32_e32 v27, v27
	s_nop 0
	v_pk_mul_f32 v[26:27], v[26:27], v[30:31]
	s_nop 0
	v_mul_f32_e32 v32, v26, v27
	v_pk_mul_f32 v[26:27], v[20:21], v[46:47]
	v_and_b32_e32 v31, 0xffff0000, v33
	v_fma_f32 v26, v13, v56, v26
	v_add_f32_e32 v26, v26, v27
	v_mul_f32_e32 v27, 0xbfb8aa3b, v31
	v_exp_f32_e32 v27, v27
	v_and_b32_e32 v30, 0xffff0000, v29
	v_mov_b64_e32 v[46:47], v[56:57]
	v_add_f32_e32 v27, 1.0, v27
	v_rcp_f32_e32 v27, v27
	s_nop 0
	v_pk_mul_f32 v[26:27], v[26:27], v[30:31]
	v_lshl_add_u64 v[30:31], v[42:43], 0, v[0:1]
	v_lshl_add_u64 v[42:43], v[42:43], 0, s[22:23]
	s_mov_b64 s[22:23], 0x5800
	v_mul_f32_e32 v29, v26, v27
	v_cvt_pk_bf16_f32 v26, v64, v65
	v_cvt_pk_bf16_f32 v27, v60, v58
	v_cvt_pk_bf16_f32 v28, v59, v28
	v_lshl_add_u64 v[44:45], v[44:45], 0, s[22:23]
	v_mov_b64_e32 v[58:59], v[52:53]
	v_mov_b64_e32 v[60:61], v[50:51]
	v_cvt_pk_bf16_f32 v29, v32, v29
	global_store_dwordx4 v[30:31], v[26:29], off
	s_cbranch_scc0 .Lconv_Y
	s_branch .Lconv_done
.Lconv_Y:
	s_mov_b64 s[22:23], 0x5800
	v_lshl_add_u64 v[100:101], v[100:101], 0, s[22:23]
	v_lshl_add_u64 v[102:103], v[102:103], 0, s[22:23]
	s_cmp_eq_u32 s0, 1
	s_cbranch_scc1 .Lconv_np_Y
	global_load_dwordx4 v[66:69], v[100:101], off offset:3072
	global_load_dwordx4 v[70:73], v[102:103], off
	global_load_dwordx4 v[74:77], v[100:101], off offset:2048
	global_load_dwordx4 v[78:81], v[102:103], off offset:1024
	s_waitcnt vmcnt(4)
	s_branch .Lconv_go_Y

; __device__ __forceinline__ unsigned cvtpk(float lo, float hi) { unsigned r; asm volatile("v_cvt_pk_bf16_f32 %0, %1, %2" : "=v"(r) : "v"(lo), "v"(hi)); return r; }
; __device__ __forceinline__ float siluf_(float x) { return x * sigmoidf_(x); }
; __device__ __forceinline__ void item_conv(const Params& p, int l, int it) {
;     ...
;     for (int i = 0; i < 16; ++i) {
;         const int r = r0 + i; float y0[8], bb[8], zz[8], o[8]; ycx(r, y0); ld8(r, C_CB, bb); ld8(r, C_CZ, zz);
; #pragma unroll
;         for (int e = 0; e < 8; ++e) { o[e] = bb[e] * (w0[e] * y2[e] + w1[e] * y1[e] + w2[e] * y0[e]) * siluf_(zz[e]); y2[e] = y1[e]; y1[e] = y0[e]; }
;         u32x4 ow = {cvtpk(o[0], o[1]), cvtpk(o[2], o[3]), cvtpk(o[4], o[5]), cvtpk(o[6], o[7])};
;         *(u32x4*)(p.ybuf + ((size_t)2 * MG + r) * 512 + cc * 8) = ow;
;     }
.Lconv_go_Y:
	v_lshl_add_u64 v[30:31], v[44:45], 0, v[0:1]
	v_add_co_u32_e32 v62, vcc, 0x1000, v30
	v_mov_b64_e32 v[50:51], v[34:35]
	s_nop 0
	v_addc_co_u32_e32 v63, vcc, 0, v31, vcc
	v_add_co_u32_e32 v64, vcc, s84, v30
	v_mov_b32_e32 v26, v82
	v_mov_b32_e32 v27, v83
	v_mov_b32_e32 v28, v84
	v_mov_b32_e32 v29, v85
	s_nop 0
	v_addc_co_u32_e32 v65, vcc, 0, v31, vcc
	v_mov_b32_e32 v30, v86
	v_mov_b32_e32 v31, v87
	v_mov_b32_e32 v32, v88
	v_mov_b32_e32 v33, v89
	v_mov_b64_e32 v[52:53], v[36:37]
	v_mov_b64_e32 v[54:55], v[38:39]
	v_mov_b64_e32 v[56:57], v[40:41]
	s_mov_b64 s[22:23], 0x400
	s_add_i32 s0, s0, -1
	s_cmp_eq_u32 s0, 0
	v_and_b32_e32 v34, 0xffff0000, v26
	v_lshlrev_b32_e32 v35, 16, v26
	v_and_b32_e32 v26, 0xffff0000, v27
	v_and_b32_e32 v36, 0xffff0000, v30
	v_lshlrev_b32_e32 v37, 16, v30
	v_lshlrev_b32_e32 v27, 16, v27
	v_and_b32_e32 v30, 0xffff0000, v31
	v_lshlrev_b32_e32 v31, 16, v31
	v_pk_mul_f32 v[34:35], v[34:35], v[36:37]
	v_pk_mul_f32 v[36:37], v[26:27], v[30:31]
	v_and_b32_e32 v26, 0xffff0000, v28
	v_lshlrev_b32_e32 v27, 16, v28
	v_and_b32_e32 v30, 0xffff0000, v32
	v_lshlrev_b32_e32 v31, 16, v32
	v_pk_mul_f32 v[38:39], v[26:27], v[30:31]
	v_and_b32_e32 v26, 0xffff0000, v29
	v_lshlrev_b32_e32 v27, 16, v29
	v_and_b32_e32 v28, 0xffff0000, v33
	v_lshlrev_b32_e32 v29, 16, v33
	v_pk_mul_f32 v[40:41], v[26:27], v[28:29]
	v_mov_b32_e32 v26, v90
	v_mov_b32_e32 v27, v91
	v_mov_b32_e32 v28, v92
	v_mov_b32_e32 v29, v93
	v_mov_b32_e32 v30, v94
	v_mov_b32_e32 v31, v95
	v_mov_b32_e32 v32, v96
	v_mov_b32_e32 v33, v97
	v_mov_b32_e32 v62, v61
	v_mov_b32_e32 v63, v35
	v_pk_mul_f32 v[62:63], v[6:7], v[62:63]
	v_lshlrev_b32_e32 v64, 16, v26
	v_fma_f32 v61, v14, v51, v62
	v_lshlrev_b32_e32 v65, 16, v30
	v_add_f32_e32 v62, v61, v63
	v_mul_f32_e32 v61, 0xbfb8aa3b, v65
	v_exp_f32_e32 v61, v61
	s_nop 0
	v_add_f32_e32 v61, 1.0, v61
	v_rcp_f32_e32 v63, v61
	v_mov_b32_e32 v61, v34
	v_pk_mul_f32 v[60:61], v[22:23], v[60:61]
	v_pk_mul_f32 v[62:63], v[62:63], v[64:65]
	s_nop 0
	v_mul_f32_e32 v64, v62, v63
	v_and_b32_e32 v63, 0xffff0000, v30
	v_and_b32_e32 v62, 0xffff0000, v26
	v_mul_f32_e32 v26, 0xbfb8aa3b, v63
	v_exp_f32_e32 v26, v26
	v_fma_f32 v60, v15, v50, v60
	v_add_f32_e32 v60, v60, v61
	v_and_b32_e32 v30, 0xffff0000, v27
	v_add_f32_e32 v26, 1.0, v26
	v_rcp_f32_e32 v61, v26
	s_nop 0
	v_pk_mul_f32 v[60:61], v[60:61], v[62:63]
	s_nop 0
	v_mul_f32_e32 v65, v60, v61
	v_mov_b32_e32 v60, v59
	v_mov_b32_e32 v61, v37
	v_lshlrev_b32_e32 v63, 16, v31
	v_and_b32_e32 v31, 0xffff0000, v31
	v_pk_mul_f32 v[60:61], v[8:9], v[60:61]
	v_lshlrev_b32_e32 v62, 16, v27
	v_mul_f32_e32 v27, 0xbfb8aa3b, v31
	v_fma_f32 v26, v16, v53, v60
	v_exp_f32_e32 v27, v27
	v_add_f32_e32 v60, v26, v61
	v_mul_f32_e32 v26, 0xbfb8aa3b, v63
	v_exp_f32_e32 v26, v26
	v_add_f32_e32 v27, 1.0, v27
	v_mov_b32_e32 v59, v36
	v_rcp_f32_e32 v27, v27
	v_add_f32_e32 v26, 1.0, v26
	v_pk_mul_f32 v[58:59], v[24:25], v[58:59]
	v_rcp_f32_e32 v61, v26
	v_fma_f32 v26, v17, v52, v58
	v_add_f32_e32 v26, v26, v59
	v_pk_mul_f32 v[26:27], v[26:27], v[30:31]
	v_lshlrev_b32_e32 v31, 16, v32
	v_mul_f32_e32 v58, v26, v27
	v_mov_b32_e32 v26, v49
	v_mov_b32_e32 v27, v39
	v_pk_mul_f32 v[26:27], v[2:3], v[26:27]
	v_lshlrev_b32_e32 v30, 16, v28
	v_fma_f32 v26, v10, v55, v26
	v_add_f32_e32 v26, v26, v27
	v_mul_f32_e32 v27, 0xbfb8aa3b, v31
	v_exp_f32_e32 v27, v27
	v_mov_b32_e32 v49, v38
	v_pk_mul_f32 v[60:61], v[60:61], v[62:63]
	v_add_f32_e32 v27, 1.0, v27
	v_rcp_f32_e32 v27, v27
	v_mul_f32_e32 v60, v60, v61
	v_pk_mul_f32 v[26:27], v[26:27], v[30:31]
	s_nop 0
	v_mul_f32_e32 v59, v26, v27
	v_pk_mul_f32 v[26:27], v[18:19], v[48:49]
	v_and_b32_e32 v31, 0xffff0000, v32
	v_fma_f32 v26, v11, v54, v26
	v_add_f32_e32 v26, v26, v27
	v_mul_f32_e32 v27, 0xbfb8aa3b, v31
	v_exp_f32_e32 v27, v27
	v_and_b32_e32 v30, 0xffff0000, v28
	v_mov_b64_e32 v[48:49], v[54:55]
	v_add_f32_e32 v27, 1.0, v27
	v_rcp_f32_e32 v27, v27
	s_nop 0
	v_pk_mul_f32 v[26:27], v[26:27], v[30:31]
	s_nop 0
	v_mul_f32_e32 v28, v26, v27
	v_mov_b32_e32 v26, v47
	v_mov_b32_e32 v27, v41
	v_pk_mul_f32 v[26:27], v[4:5], v[26:27]
	v_lshlrev_b32_e32 v31, 16, v33
	v_fma_f32 v26, v12, v57, v26
	v_add_f32_e32 v26, v26, v27
	v_mul_f32_e32 v27, 0xbfb8aa3b, v31
	v_exp_f32_e32 v27, v27
	v_lshlrev_b32_e32 v30, 16, v29
	v_mov_b32_e32 v47, v40
	v_add_f32_e32 v27, 1.0, v27
	v_rcp_f32_e32 v27, v27
	s_nop 0
	v_pk_mul_f32 v[26:27], v[26:27], v[30:31]
	s_nop 0
	v_mul_f32_e32 v32, v26, v27
	v_pk_mul_f32 v[26:27], v[20:21], v[46:47]
	v_and_b32_e32 v31, 0xffff0000, v33
	v_fma_f32 v26, v13, v56, v26
	v_add_f32_e32 v26, v26, v27
	v_mul_f32_e32 v27, 0xbfb8aa3b, v31
	v_exp_f32_e32 v27, v27
	v_and_b32_e32 v30, 0xffff0000, v29
	v_mov_b64_e32 v[46:47], v[56:57]
	v_add_f32_e32 v27, 1.0, v27
	v_rcp_f32_e32 v27, v27
	s_nop 0
	v_pk_mul_f32 v[26:27], v[26:27], v[30:31]
	v_lshl_add_u64 v[30:31], v[42:43], 0, v[0:1]
	v_lshl_add_u64 v[42:43], v[42:43], 0, s[22:23]
	s_mov_b64 s[22:23], 0x5800
	v_mul_f32_e32 v29, v26, v27
	v_cvt_pk_bf16_f32 v26, v64, v65
	v_cvt_pk_bf16_f32 v27, v60, v58
	v_cvt_pk_bf16_f32 v28, v59, v28
	v_lshl_add_u64 v[44:45], v[44:45], 0, s[22:23]
	v_mov_b64_e32 v[58:59], v[52:53]
	v_mov_b64_e32 v[60:61], v[50:51]
	v_cvt_pk_bf16_f32 v29, v32, v29
	global_store_dwordx4 v[30:31], v[26:29], off
	s_cbranch_scc0 .Lconv_X
.Lconv_done:
	s_mov_b64 s[0:1], 0
; #define LAS __attribute__((address_space(3)))
; __device__ __forceinline__ float bflo(unsigned w) { return __uint_as_float(w << 16); }
; __device__ __forceinline__ float bfhi(unsigned w) { return __uint_as_float(w & 0xffff0000u); }
; __device__ __forceinline__ int opq(int x) { asm volatile("" : "+v"(x)); return x; }
; __device__ __forceinline__ void item_gate(const Params& p, int l, int bl, int ch, LAS unsigned char* lds) {
;     const int tid = opq(threadIdx.x); const size_t r0 = (size_t)bl * SEQ + ch * 128;
;     LAS float* stats = (LAS float*)lds;
;     { const int tok = tid >> 2, part = tid & 3; const u16* vp = p.proj + (r0 + tok) * NP + C_AV + part * 128;
;       u32x4 w[16]; float s = 0.f;
; #pragma unroll
;       for (int i = 0; i < 16; ++i) { w[i] = *(const u32x4*)(vp + i * 8);
; #pragma unroll
;           for (int e = 0; e < 4; ++e) s += bflo(w[i][e]) + bfhi(w[i][e]); }
.LBB0_158:
	s_mov_b64 s[38:39], 0
	s_and_b64 vcc, exec, s[0:1]
	s_mov_b64 s[0:1], 0
	s_cbranch_vccz .LBB0_178
	v_mov_b32_e32 v18, v198
	s_and_b32 s0, s20, 0x7ff80
	v_ashrrev_i32_e32 v20, 2, v18
	s_add_i32 s30, s0, 0xfffb8000
	v_ashrrev_i32_e32 v21, 31, v20
	v_lshl_add_u64 v[2:3], v[20:21], 0, s[30:31]
	v_mov_b64_e32 v[4:5], s[14:15]
	v_and_b32_e32 v19, 3, v18
	v_mad_u64_u32 v[4:5], s[0:1], v2, s33, v[4:5]
	v_mad_i32_i24 v5, v3, s33, v5
	v_lshlrev_b32_e32 v0, 8, v19
	v_lshl_add_u64 v[14:15], v[4:5], 0, v[0:1]
	global_load_dwordx4 v[2:5], v[14:15], off offset:1072
	global_load_dwordx4 v[6:9], v[14:15], off offset:1056
	global_load_dwordx4 v[10:13], v[14:15], off offset:1040
	global_load_dwordx4 v[22:25], v[14:15], off offset:1024
	s_waitcnt vmcnt(0)
	v_lshlrev_b32_e32 v27, 16, v2
	s_waitcnt vmcnt(2)
	v_lshlrev_b32_e32 v35, 16, v6
	s_waitcnt vmcnt(1)
	v_lshlrev_b32_e32 v43, 16, v10
	s_waitcnt vmcnt(0)
	v_lshlrev_b32_e32 v51, 16, v22
	v_and_b32_e32 v50, 0xffff0000, v22
	v_add_f32_e32 v0, v51, v50
	v_lshlrev_b32_e32 v49, 16, v23
	v_and_b32_e32 v48, 0xffff0000, v23
	v_add_f32_e32 v0, 0, v0
	v_add_f32_e32 v16, v49, v48
	v_lshlrev_b32_e32 v47, 16, v24
	v_and_b32_e32 v46, 0xffff0000, v24
	v_add_f32_e32 v0, v16, v0
	v_add_f32_e32 v16, v47, v46
	v_lshlrev_b32_e32 v45, 16, v25
	v_and_b32_e32 v44, 0xffff0000, v25
	v_add_f32_e32 v0, v16, v0
	v_add_f32_e32 v16, v45, v44
	v_and_b32_e32 v42, 0xffff0000, v10
	v_add_f32_e32 v0, v16, v0
	v_add_f32_e32 v10, v43, v42
	v_lshlrev_b32_e32 v41, 16, v11
	v_and_b32_e32 v40, 0xffff0000, v11
	v_add_f32_e32 v0, v10, v0
	v_add_f32_e32 v10, v41, v40
	v_lshlrev_b32_e32 v39, 16, v12
	v_and_b32_e32 v38, 0xffff0000, v12
	v_add_f32_e32 v0, v10, v0
	v_add_f32_e32 v10, v39, v38
	v_lshlrev_b32_e32 v37, 16, v13
	v_and_b32_e32 v36, 0xffff0000, v13
	v_add_f32_e32 v0, v10, v0
	v_add_f32_e32 v10, v37, v36
	v_and_b32_e32 v34, 0xffff0000, v6
	v_add_f32_e32 v0, v10, v0
	v_add_f32_e32 v6, v35, v34
	v_lshlrev_b32_e32 v33, 16, v7
	v_and_b32_e32 v32, 0xffff0000, v7
	v_add_f32_e32 v0, v6, v0
	v_add_f32_e32 v6, v33, v32
	v_lshlrev_b32_e32 v31, 16, v8
	v_and_b32_e32 v30, 0xffff0000, v8
	v_add_f32_e32 v0, v6, v0
	v_add_f32_e32 v6, v31, v30
	v_lshlrev_b32_e32 v29, 16, v9
	v_and_b32_e32 v28, 0xffff0000, v9
	v_add_f32_e32 v0, v6, v0
	v_add_f32_e32 v6, v29, v28
	v_and_b32_e32 v26, 0xffff0000, v2
	v_add_f32_e32 v0, v6, v0
	v_add_f32_e32 v2, v27, v26
	v_lshlrev_b32_e32 v25, 16, v3
	v_and_b32_e32 v24, 0xffff0000, v3
	v_add_f32_e32 v0, v2, v0
	v_add_f32_e32 v2, v25, v24
	v_lshlrev_b32_e32 v23, 16, v4
	v_and_b32_e32 v22, 0xffff0000, v4
	v_add_f32_e32 v0, v2, v0
	v_add_f32_e32 v2, v23, v22
	v_add_f32_e32 v2, v2, v0
	v_lshlrev_b32_e32 v21, 16, v5
	v_and_b32_e32 v0, 0xffff0000, v5
	v_add_f32_e32 v3, v21, v0
	v_add_f32_e32 v16, v3, v2
	global_load_dwordx4 v[2:5], v[14:15], off offset:1136
	global_load_dwordx4 v[6:9], v[14:15], off offset:1120
	global_load_dwordx4 v[10:13], v[14:15], off offset:1104
	global_load_dwordx4 v[52:55], v[14:15], off offset:1088
	s_waitcnt vmcnt(3)
	v_lshlrev_b32_e32 v59, 16, v2
	s_waitcnt vmcnt(2)
	v_lshlrev_b32_e32 v67, 16, v6
	s_waitcnt vmcnt(1)
	v_lshlrev_b32_e32 v75, 16, v10
	s_waitcnt vmcnt(0)
	v_lshlrev_b32_e32 v83, 16, v52
	v_and_b32_e32 v82, 0xffff0000, v52
	v_add_f32_e32 v17, v83, v82
	v_lshlrev_b32_e32 v81, 16, v53
	v_and_b32_e32 v80, 0xffff0000, v53
	v_add_f32_e32 v16, v17, v16
	v_add_f32_e32 v17, v81, v80
	v_lshlrev_b32_e32 v79, 16, v54
	v_and_b32_e32 v78, 0xffff0000, v54
	v_add_f32_e32 v16, v17, v16
	v_add_f32_e32 v17, v79, v78
	v_lshlrev_b32_e32 v77, 16, v55
	v_and_b32_e32 v76, 0xffff0000, v55
	v_add_f32_e32 v16, v17, v16
	v_add_f32_e32 v17, v77, v76
	v_and_b32_e32 v74, 0xffff0000, v10
	v_add_f32_e32 v16, v17, v16
	v_add_f32_e32 v10, v75, v74
	v_lshlrev_b32_e32 v73, 16, v11
	v_and_b32_e32 v72, 0xffff0000, v11
	v_add_f32_e32 v10, v10, v16
	v_add_f32_e32 v11, v73, v72
	v_lshlrev_b32_e32 v71, 16, v12
	v_and_b32_e32 v70, 0xffff0000, v12
	v_add_f32_e32 v10, v11, v10
	v_add_f32_e32 v11, v71, v70
	v_lshlrev_b32_e32 v69, 16, v13
	v_and_b32_e32 v68, 0xffff0000, v13
	v_add_f32_e32 v10, v11, v10
	v_add_f32_e32 v11, v69, v68
	v_and_b32_e32 v66, 0xffff0000, v6
	v_add_f32_e32 v10, v11, v10
	v_add_f32_e32 v6, v67, v66
	v_lshlrev_b32_e32 v65, 16, v7
	v_and_b32_e32 v64, 0xffff0000, v7
	v_add_f32_e32 v6, v6, v10
	v_add_f32_e32 v7, v65, v64
	v_lshlrev_b32_e32 v63, 16, v8
	v_and_b32_e32 v62, 0xffff0000, v8
	v_add_f32_e32 v6, v7, v6
	v_add_f32_e32 v7, v63, v62
	v_lshlrev_b32_e32 v61, 16, v9
	v_and_b32_e32 v60, 0xffff0000, v9
	v_add_f32_e32 v6, v7, v6
	v_add_f32_e32 v7, v61, v60
	v_and_b32_e32 v58, 0xffff0000, v2
	v_add_f32_e32 v6, v7, v6
	v_add_f32_e32 v2, v59, v58
	v_lshlrev_b32_e32 v57, 16, v3
	v_and_b32_e32 v56, 0xffff0000, v3
	v_add_f32_e32 v2, v2, v6
	v_add_f32_e32 v3, v57, v56
	v_lshlrev_b32_e32 v55, 16, v4
	v_and_b32_e32 v54, 0xffff0000, v4
	v_add_f32_e32 v2, v3, v2
	v_add_f32_e32 v3, v55, v54
	v_lshlrev_b32_e32 v53, 16, v5
	v_and_b32_e32 v52, 0xffff0000, v5
	v_add_f32_e32 v2, v3, v2
	v_add_f32_e32 v3, v53, v52
	v_add_f32_e32 v16, v3, v2
	global_load_dwordx4 v[2:5], v[14:15], off offset:1200
	global_load_dwordx4 v[6:9], v[14:15], off offset:1184
	global_load_dwordx4 v[10:13], v[14:15], off offset:1168
	global_load_dwordx4 v[84:87], v[14:15], off offset:1152
	s_waitcnt vmcnt(3)
	v_lshlrev_b32_e32 v91, 16, v2
	s_waitcnt vmcnt(2)
	v_lshlrev_b32_e32 v99, 16, v6
	s_waitcnt vmcnt(1)
	v_lshlrev_b32_e32 v107, 16, v10
	s_waitcnt vmcnt(0)
; __device__ __forceinline__ float bflo(unsigned w) { return __uint_as_float(w << 16); }
; __device__ __forceinline__ float bfhi(unsigned w) { return __uint_as_float(w & 0xffff0000u); }
; __device__ __forceinline__ void item_gate(const Params& p, int l, int bl, int ch, LAS unsigned char* lds) {
;     ...
;     { const int tok = tid >> 2, part = tid & 3; const u16* vp = p.proj + (r0 + tok) * NP + C_AV + part * 128;
;       u32x4 w[16]; float s = 0.f;
; #pragma unroll
;       for (int i = 0; i < 16; ++i) { w[i] = *(const u32x4*)(vp + i * 8);
; #pragma unroll
;           for (int e = 0; e < 4; ++e) s += bflo(w[i][e]) + bfhi(w[i][e]); }
;       s += __shfl_xor(s, 1); s += __shfl_xor(s, 2); const float mean = s * (1.f / 512.f);
	v_lshlrev_b32_e32 v115, 16, v84
	v_and_b32_e32 v114, 0xffff0000, v84
	v_add_f32_e32 v17, v115, v114
	v_lshlrev_b32_e32 v113, 16, v85
	v_and_b32_e32 v112, 0xffff0000, v85
	v_add_f32_e32 v16, v17, v16
	v_add_f32_e32 v17, v113, v112
	v_lshlrev_b32_e32 v111, 16, v86
	v_and_b32_e32 v110, 0xffff0000, v86
	v_add_f32_e32 v16, v17, v16
	v_add_f32_e32 v17, v111, v110
	v_lshlrev_b32_e32 v109, 16, v87
	v_and_b32_e32 v108, 0xffff0000, v87
	v_add_f32_e32 v16, v17, v16
	v_add_f32_e32 v17, v109, v108
	v_and_b32_e32 v106, 0xffff0000, v10
	v_add_f32_e32 v16, v17, v16
	v_add_f32_e32 v10, v107, v106
	v_lshlrev_b32_e32 v105, 16, v11
	v_and_b32_e32 v104, 0xffff0000, v11
	v_add_f32_e32 v10, v10, v16
	v_add_f32_e32 v11, v105, v104
	v_lshlrev_b32_e32 v103, 16, v12
	v_and_b32_e32 v102, 0xffff0000, v12
	v_add_f32_e32 v10, v11, v10
	v_add_f32_e32 v11, v103, v102
	v_lshlrev_b32_e32 v101, 16, v13
	v_and_b32_e32 v100, 0xffff0000, v13
	v_add_f32_e32 v10, v11, v10
	v_add_f32_e32 v11, v101, v100
	v_and_b32_e32 v98, 0xffff0000, v6
	v_add_f32_e32 v10, v11, v10
	v_add_f32_e32 v6, v99, v98
	v_lshlrev_b32_e32 v97, 16, v7
	v_and_b32_e32 v96, 0xffff0000, v7
	v_add_f32_e32 v6, v6, v10
	v_add_f32_e32 v7, v97, v96
	v_lshlrev_b32_e32 v95, 16, v8
	v_and_b32_e32 v94, 0xffff0000, v8
	v_add_f32_e32 v6, v7, v6
	v_add_f32_e32 v7, v95, v94
	v_lshlrev_b32_e32 v93, 16, v9
	v_and_b32_e32 v92, 0xffff0000, v9
	v_add_f32_e32 v6, v7, v6
	v_add_f32_e32 v7, v93, v92
	v_and_b32_e32 v90, 0xffff0000, v2
	v_add_f32_e32 v6, v7, v6
	v_add_f32_e32 v2, v91, v90
	v_lshlrev_b32_e32 v89, 16, v3
	v_and_b32_e32 v88, 0xffff0000, v3
	v_add_f32_e32 v2, v2, v6
	v_add_f32_e32 v3, v89, v88
	v_lshlrev_b32_e32 v87, 16, v4
	v_and_b32_e32 v86, 0xffff0000, v4
	v_add_f32_e32 v2, v3, v2
	v_add_f32_e32 v3, v87, v86
	v_lshlrev_b32_e32 v85, 16, v5
	v_and_b32_e32 v84, 0xffff0000, v5
	v_add_f32_e32 v2, v3, v2
	v_add_f32_e32 v3, v85, v84
	v_add_f32_e32 v116, v3, v2
	global_load_dwordx4 v[2:5], v[14:15], off offset:1264
	global_load_dwordx4 v[6:9], v[14:15], off offset:1248
	global_load_dwordx4 v[10:13], v[14:15], off offset:1232
	s_nop 0
	global_load_dwordx4 v[14:17], v[14:15], off offset:1216
	s_waitcnt vmcnt(2)
	v_lshlrev_b32_e32 v133, 16, v6
	s_waitcnt vmcnt(1)
	v_lshlrev_b32_e32 v125, 16, v10
	s_waitcnt vmcnt(0)
	v_lshlrev_b32_e32 v117, 16, v14
	v_and_b32_e32 v118, 0xffff0000, v14
	v_add_f32_e32 v14, v117, v118
	v_lshlrev_b32_e32 v119, 16, v15
	v_and_b32_e32 v120, 0xffff0000, v15
	v_add_f32_e32 v14, v14, v116
	v_add_f32_e32 v15, v119, v120
	v_lshlrev_b32_e32 v121, 16, v16
	v_and_b32_e32 v122, 0xffff0000, v16
	v_add_f32_e32 v14, v15, v14
	v_add_f32_e32 v15, v121, v122
	v_lshlrev_b32_e32 v123, 16, v17
	v_and_b32_e32 v124, 0xffff0000, v17
	v_add_f32_e32 v14, v15, v14
	v_add_f32_e32 v15, v123, v124
	v_and_b32_e32 v126, 0xffff0000, v10
	v_add_f32_e32 v14, v15, v14
	v_add_f32_e32 v10, v125, v126
	v_lshlrev_b32_e32 v127, 16, v11
	v_and_b32_e32 v128, 0xffff0000, v11
	v_add_f32_e32 v10, v10, v14
	v_add_f32_e32 v11, v127, v128
	v_lshlrev_b32_e32 v129, 16, v12
	v_and_b32_e32 v130, 0xffff0000, v12
	v_add_f32_e32 v10, v11, v10
	v_add_f32_e32 v11, v129, v130
	v_lshlrev_b32_e32 v131, 16, v13
	v_and_b32_e32 v132, 0xffff0000, v13
	v_add_f32_e32 v10, v11, v10
	v_add_f32_e32 v11, v131, v132
	v_and_b32_e32 v134, 0xffff0000, v6
	v_add_f32_e32 v10, v11, v10
	v_add_f32_e32 v6, v133, v134
	v_lshlrev_b32_e32 v135, 16, v7
	v_and_b32_e32 v116, 0xffff0000, v7
	v_add_f32_e32 v6, v6, v10
	v_add_f32_e32 v7, v135, v116
	v_lshlrev_b32_e32 v17, 16, v8
	v_and_b32_e32 v16, 0xffff0000, v8
	v_add_f32_e32 v6, v7, v6
	v_add_f32_e32 v7, v17, v16
	v_lshlrev_b32_e32 v14, 16, v9
	v_and_b32_e32 v13, 0xffff0000, v9
	v_add_f32_e32 v6, v7, v6
	v_add_f32_e32 v7, v14, v13
	v_lshlrev_b32_e32 v12, 16, v2
	v_and_b32_e32 v11, 0xffff0000, v2
	v_add_f32_e32 v6, v7, v6
	v_add_f32_e32 v2, v12, v11
	v_lshlrev_b32_e32 v9, 16, v3
	v_and_b32_e32 v8, 0xffff0000, v3
	v_add_f32_e32 v2, v2, v6
	v_add_f32_e32 v3, v9, v8
	v_lshlrev_b32_e32 v7, 16, v4
	v_and_b32_e32 v6, 0xffff0000, v4
	v_add_f32_e32 v2, v3, v2
	v_add_f32_e32 v3, v7, v6
	v_add_f32_e32 v2, v3, v2
	v_lshlrev_b32_e32 v4, 16, v5
	v_and_b32_e32 v3, 0xffff0000, v5
	v_add_f32_e32 v5, v4, v3
	v_and_b32_e32 v10, 64, v206
	v_add_f32_e32 v2, v5, v2
	v_xor_b32_e32 v5, 1, v206
	v_add_u32_e32 v10, 64, v10
	v_cmp_lt_i32_e32 vcc, v5, v10
	s_nop 1
	v_cndmask_b32_e32 v5, v206, v5, vcc
	v_lshlrev_b32_e32 v5, 2, v5
	ds_bpermute_b32 v15, v5, v2
	s_waitcnt lgkmcnt(0)
	v_add_f32_e32 v2, v2, v15
	v_xor_b32_e32 v15, 2, v206
	v_cmp_lt_i32_e32 vcc, v15, v10
	s_nop 1
	v_cndmask_b32_e32 v10, v206, v15, vcc
	v_lshlrev_b32_e32 v10, 2, v10
	ds_bpermute_b32 v15, v10, v2
	v_cmp_eq_u32_e32 vcc, 0, v19
	s_waitcnt lgkmcnt(0)
; __device__ __forceinline__ float bflo(unsigned w) { return __uint_as_float(w << 16); }
; __device__ __forceinline__ float bfhi(unsigned w) { return __uint_as_float(w & 0xffff0000u); }
; __device__ __forceinline__ void item_gate(const Params& p, int l, int bl, int ch, LAS unsigned char* lds) {
;     ...
;       s += __shfl_xor(s, 1); s += __shfl_xor(s, 2); const float mean = s * (1.f / 512.f);
;       float q = 0.f;
; #pragma unroll
;       for (int i = 0; i < 16; ++i)
; #pragma unroll
;           for (int e = 0; e < 4; ++e) { const float a = bflo(w[i][e]) - mean, b = bfhi(w[i][e]) - mean; q = fmaf(a, a, q); q = fmaf(b, b, q); }
	v_add_f32_e32 v2, v2, v15
	v_fmac_f32_e32 v51, 0xbb000000, v2
	v_fmac_f32_e32 v50, 0xbb000000, v2
	v_fma_f32 v15, v51, v51, 0
	v_fmac_f32_e32 v15, v50, v50
	v_fmac_f32_e32 v49, 0xbb000000, v2
	v_fmac_f32_e32 v48, 0xbb000000, v2
	v_fmac_f32_e32 v15, v49, v49
	v_fmac_f32_e32 v15, v48, v48
	v_fmac_f32_e32 v47, 0xbb000000, v2
	v_fmac_f32_e32 v46, 0xbb000000, v2
	v_fmac_f32_e32 v15, v47, v47
	v_fmac_f32_e32 v15, v46, v46
	v_fmac_f32_e32 v45, 0xbb000000, v2
	v_fmac_f32_e32 v44, 0xbb000000, v2
	v_fmac_f32_e32 v15, v45, v45
	v_fmac_f32_e32 v15, v44, v44
	v_fmac_f32_e32 v43, 0xbb000000, v2
	v_fmac_f32_e32 v42, 0xbb000000, v2
	v_fmac_f32_e32 v15, v43, v43
	v_fmac_f32_e32 v15, v42, v42
	v_fmac_f32_e32 v41, 0xbb000000, v2
	v_fmac_f32_e32 v40, 0xbb000000, v2
	v_fmac_f32_e32 v15, v41, v41
	v_fmac_f32_e32 v15, v40, v40
	v_fmac_f32_e32 v39, 0xbb000000, v2
	v_fmac_f32_e32 v38, 0xbb000000, v2
	v_fmac_f32_e32 v15, v39, v39
	v_fmac_f32_e32 v15, v38, v38
	v_fmac_f32_e32 v37, 0xbb000000, v2
	v_fmac_f32_e32 v36, 0xbb000000, v2
	v_fmac_f32_e32 v15, v37, v37
	v_fmac_f32_e32 v15, v36, v36
	v_fmac_f32_e32 v35, 0xbb000000, v2
	v_fmac_f32_e32 v34, 0xbb000000, v2
	v_fmac_f32_e32 v15, v35, v35
	v_fmac_f32_e32 v15, v34, v34
	v_fmac_f32_e32 v33, 0xbb000000, v2
	v_fmac_f32_e32 v32, 0xbb000000, v2
	v_fmac_f32_e32 v15, v33, v33
	v_fmac_f32_e32 v15, v32, v32
	v_fmac_f32_e32 v31, 0xbb000000, v2
	v_fmac_f32_e32 v30, 0xbb000000, v2
	v_fmac_f32_e32 v15, v31, v31
	v_fmac_f32_e32 v15, v30, v30
	v_fmac_f32_e32 v29, 0xbb000000, v2
	v_fmac_f32_e32 v28, 0xbb000000, v2
	v_fmac_f32_e32 v15, v29, v29
	v_fmac_f32_e32 v15, v28, v28
	v_fmac_f32_e32 v27, 0xbb000000, v2
	v_fmac_f32_e32 v26, 0xbb000000, v2
	v_fmac_f32_e32 v15, v27, v27
	v_fmac_f32_e32 v15, v26, v26
	v_fmac_f32_e32 v25, 0xbb000000, v2
	v_fmac_f32_e32 v24, 0xbb000000, v2
	v_fmac_f32_e32 v15, v25, v25
	v_fmac_f32_e32 v15, v24, v24
	v_fmac_f32_e32 v23, 0xbb000000, v2
	v_fmac_f32_e32 v22, 0xbb000000, v2
	v_fmac_f32_e32 v15, v23, v23
	v_fmac_f32_e32 v15, v22, v22
	v_fmac_f32_e32 v21, 0xbb000000, v2
	v_fmac_f32_e32 v0, 0xbb000000, v2
	v_fmac_f32_e32 v15, v21, v21
	v_fmac_f32_e32 v15, v0, v0
	v_fmac_f32_e32 v83, 0xbb000000, v2
	v_fmac_f32_e32 v82, 0xbb000000, v2
	v_fmac_f32_e32 v15, v83, v83
	v_fmac_f32_e32 v15, v82, v82
	v_fmac_f32_e32 v81, 0xbb000000, v2
	v_fmac_f32_e32 v80, 0xbb000000, v2
	v_fmac_f32_e32 v15, v81, v81
	v_fmac_f32_e32 v15, v80, v80
	v_fmac_f32_e32 v79, 0xbb000000, v2
	v_fmac_f32_e32 v78, 0xbb000000, v2
	v_fmac_f32_e32 v15, v79, v79
	v_fmac_f32_e32 v15, v78, v78
	v_fmac_f32_e32 v77, 0xbb000000, v2
	v_fmac_f32_e32 v76, 0xbb000000, v2
	v_fmac_f32_e32 v15, v77, v77
	v_fmac_f32_e32 v15, v76, v76
	v_fmac_f32_e32 v75, 0xbb000000, v2
	v_fmac_f32_e32 v74, 0xbb000000, v2
	v_fmac_f32_e32 v15, v75, v75
	v_fmac_f32_e32 v15, v74, v74
	v_fmac_f32_e32 v73, 0xbb000000, v2
	v_fmac_f32_e32 v72, 0xbb000000, v2
	v_fmac_f32_e32 v15, v73, v73
	v_fmac_f32_e32 v15, v72, v72
	v_fmac_f32_e32 v71, 0xbb000000, v2
	v_fmac_f32_e32 v70, 0xbb000000, v2
	v_fmac_f32_e32 v15, v71, v71
	v_fmac_f32_e32 v15, v70, v70
	v_fmac_f32_e32 v69, 0xbb000000, v2
	v_fmac_f32_e32 v68, 0xbb000000, v2
	v_fmac_f32_e32 v15, v69, v69
	v_fmac_f32_e32 v15, v68, v68
	v_fmac_f32_e32 v67, 0xbb000000, v2
	v_fmac_f32_e32 v66, 0xbb000000, v2
	v_fmac_f32_e32 v15, v67, v67
	v_fmac_f32_e32 v15, v66, v66
	v_fmac_f32_e32 v65, 0xbb000000, v2
	v_fmac_f32_e32 v64, 0xbb000000, v2
	v_fmac_f32_e32 v15, v65, v65
	v_fmac_f32_e32 v15, v64, v64
	v_fmac_f32_e32 v63, 0xbb000000, v2
	v_fmac_f32_e32 v62, 0xbb000000, v2
	v_fmac_f32_e32 v15, v63, v63
	v_fmac_f32_e32 v15, v62, v62
	v_fmac_f32_e32 v61, 0xbb000000, v2
	v_fmac_f32_e32 v60, 0xbb000000, v2
	v_fmac_f32_e32 v15, v61, v61
	v_fmac_f32_e32 v15, v60, v60
	v_fmac_f32_e32 v59, 0xbb000000, v2
	v_fmac_f32_e32 v58, 0xbb000000, v2
	v_fmac_f32_e32 v15, v59, v59
	v_fmac_f32_e32 v15, v58, v58
	v_fmac_f32_e32 v57, 0xbb000000, v2
	v_fmac_f32_e32 v56, 0xbb000000, v2
	v_fmac_f32_e32 v15, v57, v57
	v_fmac_f32_e32 v15, v56, v56
	v_fmac_f32_e32 v55, 0xbb000000, v2
	v_fmac_f32_e32 v54, 0xbb000000, v2
	v_fmac_f32_e32 v15, v55, v55
	v_fmac_f32_e32 v15, v54, v54
	v_fmac_f32_e32 v53, 0xbb000000, v2
	v_fmac_f32_e32 v52, 0xbb000000, v2
	v_fmac_f32_e32 v15, v53, v53
	v_fmac_f32_e32 v15, v52, v52
	v_fmac_f32_e32 v115, 0xbb000000, v2
	v_fmac_f32_e32 v114, 0xbb000000, v2
	v_fmac_f32_e32 v15, v115, v115
	v_fmac_f32_e32 v15, v114, v114
	v_fmac_f32_e32 v113, 0xbb000000, v2
	v_fmac_f32_e32 v112, 0xbb000000, v2
	v_fmac_f32_e32 v15, v113, v113
	v_fmac_f32_e32 v15, v112, v112
	v_fmac_f32_e32 v111, 0xbb000000, v2
; __device__ __forceinline__ float bflo(unsigned w) { return __uint_as_float(w << 16); }
; __device__ __forceinline__ float bfhi(unsigned w) { return __uint_as_float(w & 0xffff0000u); }
; __device__ __forceinline__ void item_gate(const Params& p, int l, int bl, int ch, LAS unsigned char* lds) {
;     ...
;       float q = 0.f;
; #pragma unroll
;       for (int i = 0; i < 16; ++i)
; #pragma unroll
;           for (int e = 0; e < 4; ++e) { const float a = bflo(w[i][e]) - mean, b = bfhi(w[i][e]) - mean; q = fmaf(a, a, q); q = fmaf(b, b, q); }
;       q += __shfl_xor(q, 1); q += __shfl_xor(q, 2);
;       if (part == 0) { stats[tok * 2] = mean; stats[tok * 2 + 1] = rsqrtf(q * (1.f / 512.f) + EPS); } }
	v_fmac_f32_e32 v110, 0xbb000000, v2
	v_fmac_f32_e32 v15, v111, v111
	v_fmac_f32_e32 v15, v110, v110
	v_fmac_f32_e32 v109, 0xbb000000, v2
	v_fmac_f32_e32 v108, 0xbb000000, v2
	v_fmac_f32_e32 v15, v109, v109
	v_fmac_f32_e32 v15, v108, v108
	v_fmac_f32_e32 v107, 0xbb000000, v2
	v_fmac_f32_e32 v106, 0xbb000000, v2
	v_fmac_f32_e32 v15, v107, v107
	v_fmac_f32_e32 v15, v106, v106
	v_fmac_f32_e32 v105, 0xbb000000, v2
	v_fmac_f32_e32 v104, 0xbb000000, v2
	v_fmac_f32_e32 v15, v105, v105
	v_fmac_f32_e32 v15, v104, v104
	v_fmac_f32_e32 v103, 0xbb000000, v2
	v_fmac_f32_e32 v102, 0xbb000000, v2
	v_fmac_f32_e32 v15, v103, v103
	v_fmac_f32_e32 v15, v102, v102
	v_fmac_f32_e32 v101, 0xbb000000, v2
	v_fmac_f32_e32 v100, 0xbb000000, v2
	v_fmac_f32_e32 v15, v101, v101
	v_fmac_f32_e32 v15, v100, v100
	v_fmac_f32_e32 v99, 0xbb000000, v2
	v_fmac_f32_e32 v98, 0xbb000000, v2
	v_fmac_f32_e32 v15, v99, v99
	v_fmac_f32_e32 v15, v98, v98
	v_fmac_f32_e32 v97, 0xbb000000, v2
	v_fmac_f32_e32 v96, 0xbb000000, v2
	v_fmac_f32_e32 v15, v97, v97
	v_fmac_f32_e32 v15, v96, v96
	v_fmac_f32_e32 v95, 0xbb000000, v2
	v_fmac_f32_e32 v94, 0xbb000000, v2
	v_fmac_f32_e32 v15, v95, v95
	v_fmac_f32_e32 v15, v94, v94
	v_fmac_f32_e32 v93, 0xbb000000, v2
	v_fmac_f32_e32 v92, 0xbb000000, v2
	v_fmac_f32_e32 v15, v93, v93
	v_fmac_f32_e32 v15, v92, v92
	v_fmac_f32_e32 v91, 0xbb000000, v2
	v_fmac_f32_e32 v90, 0xbb000000, v2
	v_fmac_f32_e32 v15, v91, v91
	v_fmac_f32_e32 v15, v90, v90
	v_fmac_f32_e32 v89, 0xbb000000, v2
	v_fmac_f32_e32 v88, 0xbb000000, v2
	v_fmac_f32_e32 v15, v89, v89
	v_fmac_f32_e32 v15, v88, v88
	v_fmac_f32_e32 v87, 0xbb000000, v2
	v_fmac_f32_e32 v86, 0xbb000000, v2
	v_fmac_f32_e32 v15, v87, v87
	v_fmac_f32_e32 v15, v86, v86
	v_fmac_f32_e32 v85, 0xbb000000, v2
	v_fmac_f32_e32 v84, 0xbb000000, v2
	v_fmac_f32_e32 v15, v85, v85
	v_fmac_f32_e32 v15, v84, v84
	v_fmac_f32_e32 v117, 0xbb000000, v2
	v_fmac_f32_e32 v118, 0xbb000000, v2
	v_fmac_f32_e32 v15, v117, v117
	v_fmac_f32_e32 v15, v118, v118
	v_fmac_f32_e32 v119, 0xbb000000, v2
	v_fmac_f32_e32 v120, 0xbb000000, v2
	v_fmac_f32_e32 v15, v119, v119
	v_fmac_f32_e32 v15, v120, v120
	v_fmac_f32_e32 v121, 0xbb000000, v2
	v_fmac_f32_e32 v122, 0xbb000000, v2
	v_fmac_f32_e32 v15, v121, v121
	v_fmac_f32_e32 v15, v122, v122
	v_fmac_f32_e32 v123, 0xbb000000, v2
	v_fmac_f32_e32 v124, 0xbb000000, v2
	v_fmac_f32_e32 v15, v123, v123
	v_fmac_f32_e32 v15, v124, v124
	v_fmac_f32_e32 v125, 0xbb000000, v2
	v_fmac_f32_e32 v126, 0xbb000000, v2
	v_fmac_f32_e32 v15, v125, v125
	v_fmac_f32_e32 v15, v126, v126
	v_fmac_f32_e32 v127, 0xbb000000, v2
	v_fmac_f32_e32 v128, 0xbb000000, v2
	v_fmac_f32_e32 v15, v127, v127
	v_fmac_f32_e32 v15, v128, v128
	v_fmac_f32_e32 v129, 0xbb000000, v2
	v_fmac_f32_e32 v130, 0xbb000000, v2
	v_fmac_f32_e32 v15, v129, v129
	v_fmac_f32_e32 v15, v130, v130
	v_fmac_f32_e32 v131, 0xbb000000, v2
	v_fmac_f32_e32 v132, 0xbb000000, v2
	v_fmac_f32_e32 v15, v131, v131
	v_fmac_f32_e32 v15, v132, v132
	v_fmac_f32_e32 v133, 0xbb000000, v2
	v_fmac_f32_e32 v134, 0xbb000000, v2
	v_fmac_f32_e32 v15, v133, v133
	v_fmac_f32_e32 v15, v134, v134
	v_fmac_f32_e32 v135, 0xbb000000, v2
	v_fmac_f32_e32 v116, 0xbb000000, v2
	v_fmac_f32_e32 v15, v135, v135
	v_fmac_f32_e32 v15, v116, v116
	v_fmac_f32_e32 v17, 0xbb000000, v2
	v_fmac_f32_e32 v16, 0xbb000000, v2
	v_fmac_f32_e32 v15, v17, v17
	v_fmac_f32_e32 v15, v16, v16
	v_fmac_f32_e32 v14, 0xbb000000, v2
	v_fmac_f32_e32 v13, 0xbb000000, v2
	v_fmac_f32_e32 v15, v14, v14
	v_fmac_f32_e32 v15, v13, v13
	v_fmac_f32_e32 v12, 0xbb000000, v2
	v_fmac_f32_e32 v11, 0xbb000000, v2
	v_fmac_f32_e32 v15, v12, v12
	v_fmac_f32_e32 v15, v11, v11
	v_fmac_f32_e32 v9, 0xbb000000, v2
	v_fmac_f32_e32 v8, 0xbb000000, v2
	v_fmac_f32_e32 v15, v9, v9
	v_fmac_f32_e32 v15, v8, v8
	v_fmac_f32_e32 v7, 0xbb000000, v2
	v_fmac_f32_e32 v6, 0xbb000000, v2
	v_fmac_f32_e32 v15, v7, v7
	v_fmac_f32_e32 v15, v6, v6
	v_fmac_f32_e32 v4, 0xbb000000, v2
	v_fmac_f32_e32 v3, 0xbb000000, v2
	v_fmac_f32_e32 v15, v4, v4
	v_fmac_f32_e32 v15, v3, v3
	ds_bpermute_b32 v0, v5, v15
	s_waitcnt lgkmcnt(0)
	v_add_f32_e32 v0, v15, v0
	ds_bpermute_b32 v3, v10, v0
	s_and_saveexec_b64 s[0:1], vcc
	s_cbranch_execz .LBB0_161
	s_waitcnt lgkmcnt(0)
	v_add_f32_e32 v0, v0, v3
	v_fmamk_f32 v0, v0, 0x3b000000, v199
	v_mul_f32_e32 v3, 0x4b800000, v0
	v_cmp_gt_f32_e32 vcc, s85, v0
	v_mul_f32_e32 v2, 0x3b000000, v2
	v_lshl_add_u32 v4, v20, 3, 0
	v_cndmask_b32_e32 v0, v0, v3, vcc
	v_rsq_f32_e32 v0, v0
	s_nop 0
	v_mul_f32_e32 v3, 0x45800000, v0
	v_cndmask_b32_e32 v3, v0, v3, vcc
	ds_write_b64 v4, v[2:3]

; __device__ __forceinline__ float bf2f(u16 b) { return __uint_as_float(((unsigned)b) << 16); }
; __device__ __forceinline__ void item_fox(const Params& p, int l, int bl, int h, int qb, LAS unsigned char* lds) {
;     ...
;     { const float bf = p.fox_b_f[l * 4 + h]; float v[8], tot = 0.f;
; #pragma unroll
;       for (int i = 0; i < 8; ++i) { const int s = tid * 8 + i; float ls = 0.f;
;           if (s < nk) { const float xx = bf2f(prow[(size_t)s * NP + C_DF + h]) + bf; ls = fminf(xx, 0.f) - log1pf(__expf(-fabsf(xx))); }
;           tot += ls; v[i] = tot; }
.LBB0_971:
	s_lshl_b32 s0, s58, 4
	s_bfe_u32 s37, s58, 0x20002
	s_and_b32 s24, s0, 0xffffff00
	s_and_b32 s23, s58, 3
	s_sub_i32 s25, 0x1000, s24
	s_mul_i32 s0, s37, 0x5800000
	s_add_u32 s0, s14, s0
	v_readlane_b32 s20, v253, 63
	s_addc_u32 s1, s15, 0
	s_or_b32 s20, s23, s20
	s_ashr_i32 s21, s20, 31
	v_readlane_b32 s40, v253, 22
	s_lshl_b64 s[20:21], s[20:21], 2
	v_readlane_b32 s46, v253, 28
	v_readlane_b32 s47, v253, 29
	s_add_u32 s20, s46, s20
	v_mov_b32_e32 v10, v198
	s_addc_u32 s21, s47, s21
	global_load_dword v0, v1, s[20:21]
	v_lshlrev_b32_e32 v11, 3, v10
	v_readfirstlane_b32 s26, v10
	v_cmp_gt_i32_e32 vcc, s25, v11
	v_mov_b32_e32 v3, 0
	v_mov_b32_e32 v2, 0
	v_readlane_b32 s41, v253, 23
	v_readlane_b32 s42, v253, 24
	v_readlane_b32 s43, v253, 25
	v_readlane_b32 s44, v253, 26
	v_readlane_b32 s45, v253, 27
	v_readlane_b32 s48, v253, 30
	v_readlane_b32 s49, v253, 31
	v_readlane_b32 s50, v253, 32
	v_readlane_b32 s51, v253, 33
	v_readlane_b32 s52, v253, 34
	v_readlane_b32 s53, v253, 35
	v_readlane_b32 s54, v253, 36
	v_readlane_b32 s55, v253, 37
	s_and_saveexec_b64 s[20:21], vcc
	s_cbranch_execz .LBB0_973
	v_mov_b64_e32 v[4:5], s[0:1]
	v_mad_i64_i32 v[4:5], s[28:29], v11, s33, v[4:5]
	s_lshl_b32 s30, s23, 1
	v_lshl_add_u64 v[4:5], v[4:5], 0, s[30:31]
	v_add_co_u32_e32 v4, vcc, 0x1000, v4
	s_mov_b32 s22, 0xbfb8aa3b
	s_nop 0
	v_addc_co_u32_e32 v5, vcc, 0, v5, vcc
	v_mov_b32_e32 v220, v4
	v_mov_b32_e32 v221, v5
	s_mov_b64 s[28:29], 0x5800
	global_load_ushort v212, v[220:221], off offset:904
	v_lshl_add_u64 v[220:221], v[220:221], 0, s[28:29]
	global_load_ushort v213, v[220:221], off offset:904
	v_lshl_add_u64 v[220:221], v[220:221], 0, s[28:29]
	global_load_ushort v214, v[220:221], off offset:904
	v_lshl_add_u64 v[220:221], v[220:221], 0, s[28:29]
	global_load_ushort v215, v[220:221], off offset:904
	v_lshl_add_u64 v[220:221], v[220:221], 0, s[28:29]
	global_load_ushort v216, v[220:221], off offset:904
	v_lshl_add_u64 v[220:221], v[220:221], 0, s[28:29]
	global_load_ushort v217, v[220:221], off offset:904
	v_lshl_add_u64 v[220:221], v[220:221], 0, s[28:29]
	global_load_ushort v218, v[220:221], off offset:904
	v_lshl_add_u64 v[220:221], v[220:221], 0, s[28:29]
	global_load_ushort v219, v[220:221], off offset:904
	s_waitcnt vmcnt(7)
	v_mov_b32_e32 v2, v212
	v_lshlrev_b32_e32 v2, 16, v2
	v_add_f32_e32 v4, v0, v2
	v_min_f32_e32 v2, 0, v4
	v_mul_f32_e64 v4, |v4|, s22
	v_exp_f32_e32 v4, v4
	s_mov_b32 s22, 0x3f2aaaab
	v_add_f32_e32 v5, 1.0, v4
	v_add_f32_e32 v6, -1.0, v5
	v_sub_f32_e32 v7, v6, v5
	v_add_f32_e32 v7, 1.0, v7
	v_sub_f32_e32 v6, v4, v6
	v_add_f32_e32 v8, v6, v7
	v_frexp_mant_f32_e32 v6, v5
	v_cmp_gt_f32_e32 vcc, s22, v6
	v_cvt_f64_f32_e32 v[6:7], v5
	v_frexp_exp_i32_f64_e32 v6, v[6:7]
	v_subbrev_co_u32_e32 v16, vcc, 0, v6, vcc
	v_sub_u32_e32 v6, 0, v16
	v_ldexp_f32 v5, v5, v6
	v_ldexp_f32 v6, v8, v6
	v_add_f32_e32 v8, -1.0, v5
	v_add_f32_e32 v7, 1.0, v8
	v_sub_f32_e32 v7, v5, v7
	v_add_f32_e32 v9, v6, v7
	v_add_f32_e32 v7, 1.0, v5
	v_add_f32_e32 v12, -1.0, v7
	v_sub_f32_e32 v5, v5, v12
	v_add_f32_e32 v5, v6, v5
	v_add_f32_e32 v17, v7, v5
	v_rcp_f32_e32 v18, v17
	v_sub_f32_e32 v6, v17, v7
	v_add_f32_e32 v7, v8, v9
	v_sub_f32_e32 v5, v5, v6
	v_mul_f32_e32 v20, v7, v18
	v_sub_f32_e32 v6, v7, v8
	v_mul_f32_e32 v8, v17, v20
	v_fma_f32 v12, v20, v17, -v8
	v_fmac_f32_e32 v12, v20, v5
	v_sub_f32_e32 v19, v9, v6
	v_add_f32_e32 v6, v8, v12
	v_sub_f32_e32 v9, v7, v6
	v_pk_add_f32 v[14:15], v[6:7], v[8:9] neg_lo:[0,1] neg_hi:[0,1]
	v_mov_b32_e32 v13, v6
	v_pk_add_f32 v[6:7], v[14:15], v[12:13] neg_lo:[0,1] neg_hi:[0,1]
	s_mov_b32 s22, 0x3f317218
	v_add_f32_e32 v7, v19, v7
	v_add_f32_e32 v6, v6, v7
	v_add_f32_e32 v7, v9, v6
	v_mul_f32_e32 v19, v18, v7
	v_mul_f32_e32 v8, v17, v19
	v_fma_f32 v12, v19, v17, -v8
	v_fmac_f32_e32 v12, v19, v5
	v_sub_f32_e32 v5, v9, v7
	v_add_f32_e32 v5, v6, v5
	v_add_f32_e32 v6, v8, v12
	v_sub_f32_e32 v9, v7, v6
	v_pk_add_f32 v[14:15], v[6:7], v[8:9] neg_lo:[0,1] neg_hi:[0,1]
	v_mov_b32_e32 v13, v6
	v_pk_add_f32 v[6:7], v[14:15], v[12:13] neg_lo:[0,1] neg_hi:[0,1]
	s_nop 0
	v_add_f32_e32 v5, v5, v7
	v_add_f32_e32 v5, v6, v5
	v_add_f32_e32 v7, v20, v19
	v_add_f32_e32 v5, v9, v5
	v_sub_f32_e32 v6, v7, v20
	v_mul_f32_e32 v5, v18, v5
	v_sub_f32_e32 v6, v19, v6
	v_add_f32_e32 v5, v6, v5
	v_add_f32_e32 v8, v7, v5
	v_mul_f32_e32 v12, v8, v8
	v_fmamk_f32 v6, v12, 0x3e9b6dac, v201
	v_fmaak_f32 v163, v12, v6, 0x3f2aaada
	v_cvt_f32_i32_e32 v6, v16
	v_sub_f32_e32 v7, v8, v7
	v_sub_f32_e32 v5, v5, v7
	v_mul_f32_e32 v7, v8, v12
	v_pk_mul_f32 v[12:13], v[6:7], v[162:163]
	v_ldexp_f32 v9, v8, 1
	v_fma_f32 v8, v6, s22, -v12
	v_fmac_f32_e32 v8, 0xb102e308, v6
	v_pk_add_f32 v[6:7], v[12:13], v[8:9]
	v_ldexp_f32 v5, v5, 1
	v_sub_f32_e32 v9, v7, v9
	v_sub_f32_e32 v9, v13, v9
	v_add_f32_e32 v15, v5, v9
	v_mov_b32_e32 v14, v12
	v_pk_add_f32 v[12:13], v[6:7], v[12:13] neg_lo:[0,1] neg_hi:[0,1]
	v_pk_add_f32 v[16:17], v[6:7], v[14:15]
	v_mov_b32_e32 v9, v6
	v_mov_b32_e32 v13, v17
	v_pk_add_f32 v[18:19], v[8:9], v[12:13] neg_lo:[0,1] neg_hi:[0,1]
	v_pk_add_f32 v[8:9], v[8:9], v[12:13]
	v_mov_b32_e32 v14, v15
	v_pk_add_f32 v[12:13], v[8:9], v[6:7] op_sel:[1,0] op_sel_hi:[0,1] neg_lo:[0,1] neg_hi:[0,1]
	v_pk_add_f32 v[20:21], v[16:17], v[12:13] op_sel_hi:[1,0] neg_lo:[0,1] neg_hi:[0,1]
	v_mov_b32_e32 v16, v17
	v_mov_b32_e32 v17, v9
	v_pk_mov_b32 v[12:13], v[6:7], v[12:13] op_sel:[1,0]
	v_mov_b32_e32 v15, v6
	v_pk_add_f32 v[12:13], v[16:17], v[12:13] neg_lo:[0,1] neg_hi:[0,1]
	v_mov_b32_e32 v20, v18
	v_pk_add_f32 v[6:7], v[14:15], v[12:13] neg_lo:[0,1] neg_hi:[0,1]
	v_mov_b32_e32 v19, v9
	v_pk_add_f32 v[12:13], v[20:21], v[6:7]
	s_mov_b32 s22, 0x7f800000
	v_pk_add_f32 v[14:15], v[12:13], v[12:13] op_sel:[0,1] op_sel_hi:[1,0]
	v_cmp_neq_f32_e32 vcc, s22, v4
	v_pk_add_f32 v[8:9], v[8:9], v[14:15] op_sel:[1,0] op_sel_hi:[0,1]
	v_mov_b32_e32 v13, v8
	v_pk_add_f32 v[16:17], v[12:13], v[18:19] neg_lo:[0,1] neg_hi:[0,1]
	v_mov_b32_e32 v7, v14
	v_sub_f32_e32 v5, v12, v16
	v_pk_add_f32 v[6:7], v[6:7], v[16:17] neg_lo:[0,1] neg_hi:[0,1]
	v_sub_f32_e32 v5, v18, v5
	v_add_f32_e32 v5, v6, v5
	v_add_f32_e32 v5, v5, v7
	v_add_f32_e32 v5, v8, v5
	v_cndmask_b32_e32 v5, v209, v5, vcc
	v_cmp_ngt_f32_e32 vcc, -1.0, v4
	s_mov_b32 s22, 0x33800000
	s_nop 0
	v_cndmask_b32_e32 v5, v210, v5, vcc
	v_cmp_neq_f32_e32 vcc, -1.0, v4
	s_nop 1
	v_cndmask_b32_e32 v5, v208, v5, vcc
	v_cmp_lt_f32_e64 vcc, |v4|, s22
	s_nop 1
	v_cndmask_b32_e32 v4, v5, v4, vcc
	v_sub_f32_e32 v2, v2, v4
	v_add_f32_e32 v2, 0, v2
; __device__ __forceinline__ float bf2f(u16 b) { return __uint_as_float(((unsigned)b) << 16); }
; __device__ __forceinline__ void item_fox(const Params& p, int l, int bl, int h, int qb, LAS unsigned char* lds) {
;     ...
;     { const float bf = p.fox_b_f[l * 4 + h]; float v[8], tot = 0.f;
; #pragma unroll
;       for (int i = 0; i < 8; ++i) { const int s = tid * 8 + i; float ls = 0.f;
;           if (s < nk) { const float xx = bf2f(prow[(size_t)s * NP + C_DF + h]) + bf; ls = fminf(xx, 0.f) - log1pf(__expf(-fabsf(xx))); }
;           tot += ls; v[i] = tot; }
.LBB0_973:
	s_or_b64 exec, exec, s[20:21]
	v_or_b32_e32 v4, 1, v11
	v_cmp_gt_i32_e32 vcc, s25, v4
	s_and_saveexec_b64 s[20:21], vcc
	s_cbranch_execz .LBB0_975
	v_mov_b64_e32 v[6:7], s[0:1]
	v_mad_i64_i32 v[4:5], s[28:29], v4, s33, v[6:7]
	s_lshl_b32 s30, s23, 1
	v_lshl_add_u64 v[4:5], v[4:5], 0, s[30:31]
	v_add_co_u32_e32 v4, vcc, 0x1000, v4
	s_mov_b32 s22, 0xbfb8aa3b
	s_nop 0
	v_addc_co_u32_e32 v5, vcc, 0, v5, vcc
	s_waitcnt vmcnt(6)
	v_mov_b32_e32 v3, v213
	v_lshlrev_b32_e32 v3, 16, v3
	v_add_f32_e32 v4, v0, v3
	v_min_f32_e32 v3, 0, v4
	v_mul_f32_e64 v4, |v4|, s22
	v_exp_f32_e32 v4, v4
	s_mov_b32 s22, 0x3f2aaaab
	v_add_f32_e32 v5, 1.0, v4
	v_add_f32_e32 v6, -1.0, v5
	v_sub_f32_e32 v7, v6, v5
	v_add_f32_e32 v7, 1.0, v7
	v_sub_f32_e32 v6, v4, v6
	v_add_f32_e32 v8, v6, v7
	v_frexp_mant_f32_e32 v6, v5
	v_cmp_gt_f32_e32 vcc, s22, v6
	v_cvt_f64_f32_e32 v[6:7], v5
	v_frexp_exp_i32_f64_e32 v6, v[6:7]
	v_subbrev_co_u32_e32 v16, vcc, 0, v6, vcc
	v_sub_u32_e32 v6, 0, v16
	v_ldexp_f32 v5, v5, v6
	v_ldexp_f32 v6, v8, v6
	v_add_f32_e32 v8, -1.0, v5
	v_add_f32_e32 v7, 1.0, v8
	v_sub_f32_e32 v7, v5, v7
	v_add_f32_e32 v9, v6, v7
	v_add_f32_e32 v7, 1.0, v5
	v_add_f32_e32 v12, -1.0, v7
	v_sub_f32_e32 v5, v5, v12
	v_add_f32_e32 v5, v6, v5
	v_add_f32_e32 v17, v7, v5
	v_rcp_f32_e32 v18, v17
	v_sub_f32_e32 v6, v17, v7
	v_add_f32_e32 v7, v8, v9
	v_sub_f32_e32 v5, v5, v6
	v_mul_f32_e32 v20, v7, v18
	v_sub_f32_e32 v6, v7, v8
	v_mul_f32_e32 v8, v17, v20
	v_fma_f32 v12, v20, v17, -v8
	v_fmac_f32_e32 v12, v20, v5
	v_sub_f32_e32 v19, v9, v6
	v_add_f32_e32 v6, v8, v12
	v_sub_f32_e32 v9, v7, v6
	v_pk_add_f32 v[14:15], v[6:7], v[8:9] neg_lo:[0,1] neg_hi:[0,1]
	v_mov_b32_e32 v13, v6
	v_pk_add_f32 v[6:7], v[14:15], v[12:13] neg_lo:[0,1] neg_hi:[0,1]
	s_mov_b32 s22, 0x3f317218
	v_add_f32_e32 v7, v19, v7
	v_add_f32_e32 v6, v6, v7
	v_add_f32_e32 v7, v9, v6
	v_mul_f32_e32 v19, v18, v7
	v_mul_f32_e32 v8, v17, v19
	v_fma_f32 v12, v19, v17, -v8
	v_fmac_f32_e32 v12, v19, v5
	v_sub_f32_e32 v5, v9, v7
	v_add_f32_e32 v5, v6, v5
	v_add_f32_e32 v6, v8, v12
	v_sub_f32_e32 v9, v7, v6
	v_pk_add_f32 v[14:15], v[6:7], v[8:9] neg_lo:[0,1] neg_hi:[0,1]
	v_mov_b32_e32 v13, v6
	v_pk_add_f32 v[6:7], v[14:15], v[12:13] neg_lo:[0,1] neg_hi:[0,1]
	s_nop 0
	v_add_f32_e32 v5, v5, v7
	v_add_f32_e32 v5, v6, v5
	v_add_f32_e32 v7, v20, v19
	v_add_f32_e32 v5, v9, v5
	v_sub_f32_e32 v6, v7, v20
	v_mul_f32_e32 v5, v18, v5
	v_sub_f32_e32 v6, v19, v6
	v_add_f32_e32 v5, v6, v5
	v_add_f32_e32 v8, v7, v5
	v_mul_f32_e32 v12, v8, v8
	v_fmamk_f32 v6, v12, 0x3e9b6dac, v201
	v_fmaak_f32 v163, v12, v6, 0x3f2aaada
	v_cvt_f32_i32_e32 v6, v16
	v_sub_f32_e32 v7, v8, v7
	v_sub_f32_e32 v5, v5, v7
	v_mul_f32_e32 v7, v8, v12
	v_pk_mul_f32 v[12:13], v[6:7], v[162:163]
	v_ldexp_f32 v9, v8, 1
	v_fma_f32 v8, v6, s22, -v12
	v_fmac_f32_e32 v8, 0xb102e308, v6
	v_pk_add_f32 v[6:7], v[12:13], v[8:9]
	v_ldexp_f32 v5, v5, 1
	v_sub_f32_e32 v9, v7, v9
	v_sub_f32_e32 v9, v13, v9
	v_add_f32_e32 v15, v5, v9
	v_mov_b32_e32 v14, v12
	v_pk_add_f32 v[12:13], v[6:7], v[12:13] neg_lo:[0,1] neg_hi:[0,1]
	v_pk_add_f32 v[16:17], v[6:7], v[14:15]
	v_mov_b32_e32 v9, v6
	v_mov_b32_e32 v13, v17
	v_pk_add_f32 v[18:19], v[8:9], v[12:13] neg_lo:[0,1] neg_hi:[0,1]
	v_pk_add_f32 v[8:9], v[8:9], v[12:13]
	v_mov_b32_e32 v14, v15
	v_pk_add_f32 v[12:13], v[8:9], v[6:7] op_sel:[1,0] op_sel_hi:[0,1] neg_lo:[0,1] neg_hi:[0,1]
	v_pk_add_f32 v[20:21], v[16:17], v[12:13] op_sel_hi:[1,0] neg_lo:[0,1] neg_hi:[0,1]
	v_mov_b32_e32 v16, v17
	v_mov_b32_e32 v17, v9
	v_pk_mov_b32 v[12:13], v[6:7], v[12:13] op_sel:[1,0]
	v_mov_b32_e32 v15, v6
	v_pk_add_f32 v[12:13], v[16:17], v[12:13] neg_lo:[0,1] neg_hi:[0,1]
	v_mov_b32_e32 v20, v18
	v_pk_add_f32 v[6:7], v[14:15], v[12:13] neg_lo:[0,1] neg_hi:[0,1]
	v_mov_b32_e32 v19, v9
	v_pk_add_f32 v[12:13], v[20:21], v[6:7]
	s_mov_b32 s22, 0x7f800000
	v_pk_add_f32 v[14:15], v[12:13], v[12:13] op_sel:[0,1] op_sel_hi:[1,0]
	v_cmp_neq_f32_e32 vcc, s22, v4
	v_pk_add_f32 v[8:9], v[8:9], v[14:15] op_sel:[1,0] op_sel_hi:[0,1]
	v_mov_b32_e32 v13, v8
	v_pk_add_f32 v[16:17], v[12:13], v[18:19] neg_lo:[0,1] neg_hi:[0,1]
	v_mov_b32_e32 v7, v14
	v_sub_f32_e32 v5, v12, v16
	v_pk_add_f32 v[6:7], v[6:7], v[16:17] neg_lo:[0,1] neg_hi:[0,1]
	v_sub_f32_e32 v5, v18, v5
	v_add_f32_e32 v5, v6, v5
	v_add_f32_e32 v5, v5, v7
	v_add_f32_e32 v5, v8, v5
	v_cndmask_b32_e32 v5, v209, v5, vcc
	v_cmp_ngt_f32_e32 vcc, -1.0, v4
	s_mov_b32 s22, 0x33800000
	s_nop 0
	v_cndmask_b32_e32 v5, v210, v5, vcc
	v_cmp_neq_f32_e32 vcc, -1.0, v4
	s_nop 1
	v_cndmask_b32_e32 v5, v208, v5, vcc
	v_cmp_lt_f32_e64 vcc, |v4|, s22
	s_nop 1
	v_cndmask_b32_e32 v4, v5, v4, vcc
	v_sub_f32_e32 v3, v3, v4
; __device__ __forceinline__ float bf2f(u16 b) { return __uint_as_float(((unsigned)b) << 16); }
; __device__ __forceinline__ void item_fox(const Params& p, int l, int bl, int h, int qb, LAS unsigned char* lds) {
;     ...
;     { const float bf = p.fox_b_f[l * 4 + h]; float v[8], tot = 0.f;
; #pragma unroll
;       for (int i = 0; i < 8; ++i) { const int s = tid * 8 + i; float ls = 0.f;
;           if (s < nk) { const float xx = bf2f(prow[(size_t)s * NP + C_DF + h]) + bf; ls = fminf(xx, 0.f) - log1pf(__expf(-fabsf(xx))); }
;           tot += ls; v[i] = tot; }
.LBB0_975:
	s_or_b64 exec, exec, s[20:21]
	v_or_b32_e32 v6, 2, v11
	v_cmp_gt_i32_e32 vcc, s25, v6
	v_mov_b32_e32 v4, 0
	v_mov_b32_e32 v5, 0
	s_and_saveexec_b64 s[20:21], vcc
	s_cbranch_execz .LBB0_977
	v_mov_b64_e32 v[8:9], s[0:1]
	v_mad_i64_i32 v[6:7], s[28:29], v6, s33, v[8:9]
	s_lshl_b32 s30, s23, 1
	v_lshl_add_u64 v[6:7], v[6:7], 0, s[30:31]
	v_add_co_u32_e32 v6, vcc, 0x1000, v6
	s_mov_b32 s22, 0xbfb8aa3b
	s_nop 0
	v_addc_co_u32_e32 v7, vcc, 0, v7, vcc
	s_waitcnt vmcnt(5)
	v_mov_b32_e32 v5, v214
	v_lshlrev_b32_e32 v5, 16, v5
	v_add_f32_e32 v6, v0, v5
	v_min_f32_e32 v5, 0, v6
	v_mul_f32_e64 v6, |v6|, s22
	v_exp_f32_e32 v6, v6
	s_mov_b32 s22, 0x3f2aaaab
	v_add_f32_e32 v7, 1.0, v6
	v_add_f32_e32 v8, -1.0, v7
	v_sub_f32_e32 v9, v8, v7
	v_add_f32_e32 v9, 1.0, v9
	v_sub_f32_e32 v8, v6, v8
	v_add_f32_e32 v12, v8, v9
	v_frexp_mant_f32_e32 v8, v7
	v_cmp_gt_f32_e32 vcc, s22, v8
	v_cvt_f64_f32_e32 v[8:9], v7
	v_frexp_exp_i32_f64_e32 v8, v[8:9]
	v_subbrev_co_u32_e32 v18, vcc, 0, v8, vcc
	v_sub_u32_e32 v8, 0, v18
	v_ldexp_f32 v7, v7, v8
	v_ldexp_f32 v8, v12, v8
	v_add_f32_e32 v12, -1.0, v7
	v_add_f32_e32 v9, 1.0, v12
	v_sub_f32_e32 v9, v7, v9
	v_add_f32_e32 v13, v8, v9
	v_add_f32_e32 v9, 1.0, v7
	v_add_f32_e32 v14, -1.0, v9
	v_sub_f32_e32 v7, v7, v14
	v_add_f32_e32 v7, v8, v7
	v_add_f32_e32 v19, v9, v7
	v_rcp_f32_e32 v20, v19
	v_sub_f32_e32 v8, v19, v9
	v_add_f32_e32 v9, v12, v13
	v_sub_f32_e32 v7, v7, v8
	v_mul_f32_e32 v22, v9, v20
	v_sub_f32_e32 v8, v9, v12
	v_mul_f32_e32 v12, v19, v22
	v_fma_f32 v14, v22, v19, -v12
	v_fmac_f32_e32 v14, v22, v7
	v_sub_f32_e32 v21, v13, v8
	v_add_f32_e32 v8, v12, v14
	v_sub_f32_e32 v13, v9, v8
	v_pk_add_f32 v[16:17], v[8:9], v[12:13] neg_lo:[0,1] neg_hi:[0,1]
	v_mov_b32_e32 v15, v8
	v_pk_add_f32 v[8:9], v[16:17], v[14:15] neg_lo:[0,1] neg_hi:[0,1]
	s_mov_b32 s22, 0x3f317218
	v_add_f32_e32 v9, v21, v9
	v_add_f32_e32 v8, v8, v9
	v_add_f32_e32 v9, v13, v8
	v_mul_f32_e32 v21, v20, v9
	v_mul_f32_e32 v12, v19, v21
	v_fma_f32 v14, v21, v19, -v12
	v_fmac_f32_e32 v14, v21, v7
	v_sub_f32_e32 v7, v13, v9
	v_add_f32_e32 v7, v8, v7
	v_add_f32_e32 v8, v12, v14
	v_sub_f32_e32 v13, v9, v8
	v_pk_add_f32 v[16:17], v[8:9], v[12:13] neg_lo:[0,1] neg_hi:[0,1]
	v_mov_b32_e32 v15, v8
	v_pk_add_f32 v[8:9], v[16:17], v[14:15] neg_lo:[0,1] neg_hi:[0,1]
	s_nop 0
	v_add_f32_e32 v7, v7, v9
	v_add_f32_e32 v7, v8, v7
	v_add_f32_e32 v9, v22, v21
	v_add_f32_e32 v7, v13, v7
	v_sub_f32_e32 v8, v9, v22
	v_mul_f32_e32 v7, v20, v7
	v_sub_f32_e32 v8, v21, v8
	v_add_f32_e32 v7, v8, v7
	v_add_f32_e32 v12, v9, v7
	v_mul_f32_e32 v14, v12, v12
	v_fmamk_f32 v8, v14, 0x3e9b6dac, v201
	v_fmaak_f32 v163, v14, v8, 0x3f2aaada
	v_cvt_f32_i32_e32 v8, v18
	v_sub_f32_e32 v9, v12, v9
	v_sub_f32_e32 v7, v7, v9
	v_mul_f32_e32 v9, v12, v14
	v_pk_mul_f32 v[14:15], v[8:9], v[162:163]
	v_ldexp_f32 v13, v12, 1
	v_fma_f32 v12, v8, s22, -v14
	v_fmac_f32_e32 v12, 0xb102e308, v8
	v_pk_add_f32 v[8:9], v[14:15], v[12:13]
	v_ldexp_f32 v7, v7, 1
	v_sub_f32_e32 v13, v9, v13
	v_sub_f32_e32 v13, v15, v13
	v_add_f32_e32 v17, v7, v13
	v_mov_b32_e32 v16, v14
	v_pk_add_f32 v[14:15], v[8:9], v[14:15] neg_lo:[0,1] neg_hi:[0,1]
	v_pk_add_f32 v[18:19], v[8:9], v[16:17]
	v_mov_b32_e32 v13, v8
	v_mov_b32_e32 v15, v19
	v_pk_add_f32 v[20:21], v[12:13], v[14:15] neg_lo:[0,1] neg_hi:[0,1]
	v_pk_add_f32 v[12:13], v[12:13], v[14:15]
	v_mov_b32_e32 v16, v17
	v_pk_add_f32 v[14:15], v[12:13], v[8:9] op_sel:[1,0] op_sel_hi:[0,1] neg_lo:[0,1] neg_hi:[0,1]
	v_pk_add_f32 v[22:23], v[18:19], v[14:15] op_sel_hi:[1,0] neg_lo:[0,1] neg_hi:[0,1]
	v_mov_b32_e32 v18, v19
	v_mov_b32_e32 v19, v13
	v_pk_mov_b32 v[14:15], v[8:9], v[14:15] op_sel:[1,0]
	v_mov_b32_e32 v17, v8
	v_pk_add_f32 v[14:15], v[18:19], v[14:15] neg_lo:[0,1] neg_hi:[0,1]
	v_mov_b32_e32 v22, v20
	v_pk_add_f32 v[8:9], v[16:17], v[14:15] neg_lo:[0,1] neg_hi:[0,1]
	v_mov_b32_e32 v21, v13
	v_pk_add_f32 v[14:15], v[22:23], v[8:9]
	s_mov_b32 s22, 0x7f800000
	v_pk_add_f32 v[16:17], v[14:15], v[14:15] op_sel:[0,1] op_sel_hi:[1,0]
	v_cmp_neq_f32_e32 vcc, s22, v6
	v_pk_add_f32 v[12:13], v[12:13], v[16:17] op_sel:[1,0] op_sel_hi:[0,1]
	v_mov_b32_e32 v15, v12
	v_pk_add_f32 v[18:19], v[14:15], v[20:21] neg_lo:[0,1] neg_hi:[0,1]
	v_mov_b32_e32 v9, v16
	v_sub_f32_e32 v7, v14, v18
	v_pk_add_f32 v[8:9], v[8:9], v[18:19] neg_lo:[0,1] neg_hi:[0,1]
	v_sub_f32_e32 v7, v20, v7
	v_add_f32_e32 v7, v8, v7
	v_add_f32_e32 v7, v7, v9
	v_add_f32_e32 v7, v12, v7
	v_cndmask_b32_e32 v7, v209, v7, vcc
	v_cmp_ngt_f32_e32 vcc, -1.0, v6
	s_mov_b32 s22, 0x33800000
	s_nop 0
	v_cndmask_b32_e32 v7, v210, v7, vcc
	v_cmp_neq_f32_e32 vcc, -1.0, v6
	s_nop 1
	v_cndmask_b32_e32 v7, v208, v7, vcc
	v_cmp_lt_f32_e64 vcc, |v6|, s22
	s_nop 1
	v_cndmask_b32_e32 v6, v7, v6, vcc
	v_sub_f32_e32 v5, v5, v6
; __device__ __forceinline__ float bf2f(u16 b) { return __uint_as_float(((unsigned)b) << 16); }
; __device__ __forceinline__ void item_fox(const Params& p, int l, int bl, int h, int qb, LAS unsigned char* lds) {
;     ...
;     { const float bf = p.fox_b_f[l * 4 + h]; float v[8], tot = 0.f;
; #pragma unroll
;       for (int i = 0; i < 8; ++i) { const int s = tid * 8 + i; float ls = 0.f;
;           if (s < nk) { const float xx = bf2f(prow[(size_t)s * NP + C_DF + h]) + bf; ls = fminf(xx, 0.f) - log1pf(__expf(-fabsf(xx))); }
;           tot += ls; v[i] = tot; }
.LBB0_977:
	s_or_b64 exec, exec, s[20:21]
	v_or_b32_e32 v6, 3, v11
	v_cmp_gt_i32_e32 vcc, s25, v6
	s_and_saveexec_b64 s[20:21], vcc
	s_cbranch_execz .LBB0_979
	v_mov_b64_e32 v[8:9], s[0:1]
	v_mad_i64_i32 v[6:7], s[28:29], v6, s33, v[8:9]
	s_lshl_b32 s30, s23, 1
	v_lshl_add_u64 v[6:7], v[6:7], 0, s[30:31]
	v_add_co_u32_e32 v6, vcc, 0x1000, v6
	s_mov_b32 s22, 0xbfb8aa3b
	s_nop 0
	v_addc_co_u32_e32 v7, vcc, 0, v7, vcc
	s_waitcnt vmcnt(4)
	v_mov_b32_e32 v4, v215
	v_lshlrev_b32_e32 v4, 16, v4
	v_add_f32_e32 v6, v0, v4
	v_min_f32_e32 v4, 0, v6
	v_mul_f32_e64 v6, |v6|, s22
	v_exp_f32_e32 v6, v6
	s_mov_b32 s22, 0x3f2aaaab
	v_add_f32_e32 v7, 1.0, v6
	v_add_f32_e32 v8, -1.0, v7
	v_sub_f32_e32 v9, v8, v7
	v_add_f32_e32 v9, 1.0, v9
	v_sub_f32_e32 v8, v6, v8
	v_add_f32_e32 v12, v8, v9
	v_frexp_mant_f32_e32 v8, v7
	v_cmp_gt_f32_e32 vcc, s22, v8
	v_cvt_f64_f32_e32 v[8:9], v7
	v_frexp_exp_i32_f64_e32 v8, v[8:9]
	v_subbrev_co_u32_e32 v18, vcc, 0, v8, vcc
	v_sub_u32_e32 v8, 0, v18
	v_ldexp_f32 v7, v7, v8
	v_ldexp_f32 v8, v12, v8
	v_add_f32_e32 v12, -1.0, v7
	v_add_f32_e32 v9, 1.0, v12
	v_sub_f32_e32 v9, v7, v9
	v_add_f32_e32 v13, v8, v9
	v_add_f32_e32 v9, 1.0, v7
	v_add_f32_e32 v14, -1.0, v9
	v_sub_f32_e32 v7, v7, v14
	v_add_f32_e32 v7, v8, v7
	v_add_f32_e32 v19, v9, v7
	v_rcp_f32_e32 v20, v19
	v_sub_f32_e32 v8, v19, v9
	v_add_f32_e32 v9, v12, v13
	v_sub_f32_e32 v7, v7, v8
	v_mul_f32_e32 v22, v9, v20
	v_sub_f32_e32 v8, v9, v12
	v_mul_f32_e32 v12, v19, v22
	v_fma_f32 v14, v22, v19, -v12
	v_fmac_f32_e32 v14, v22, v7
	v_sub_f32_e32 v21, v13, v8
	v_add_f32_e32 v8, v12, v14
	v_sub_f32_e32 v13, v9, v8
	v_pk_add_f32 v[16:17], v[8:9], v[12:13] neg_lo:[0,1] neg_hi:[0,1]
	v_mov_b32_e32 v15, v8
	v_pk_add_f32 v[8:9], v[16:17], v[14:15] neg_lo:[0,1] neg_hi:[0,1]
	s_mov_b32 s22, 0x3f317218
	v_add_f32_e32 v9, v21, v9
	v_add_f32_e32 v8, v8, v9
	v_add_f32_e32 v9, v13, v8
	v_mul_f32_e32 v21, v20, v9
	v_mul_f32_e32 v12, v19, v21
	v_fma_f32 v14, v21, v19, -v12
	v_fmac_f32_e32 v14, v21, v7
	v_sub_f32_e32 v7, v13, v9
	v_add_f32_e32 v7, v8, v7
	v_add_f32_e32 v8, v12, v14
	v_sub_f32_e32 v13, v9, v8
	v_pk_add_f32 v[16:17], v[8:9], v[12:13] neg_lo:[0,1] neg_hi:[0,1]
	v_mov_b32_e32 v15, v8
	v_pk_add_f32 v[8:9], v[16:17], v[14:15] neg_lo:[0,1] neg_hi:[0,1]
	s_nop 0
	v_add_f32_e32 v7, v7, v9
	v_add_f32_e32 v7, v8, v7
	v_add_f32_e32 v9, v22, v21
	v_add_f32_e32 v7, v13, v7
	v_sub_f32_e32 v8, v9, v22
	v_mul_f32_e32 v7, v20, v7
	v_sub_f32_e32 v8, v21, v8
	v_add_f32_e32 v7, v8, v7
	v_add_f32_e32 v12, v9, v7
	v_mul_f32_e32 v14, v12, v12
	v_fmamk_f32 v8, v14, 0x3e9b6dac, v201
	v_fmaak_f32 v163, v14, v8, 0x3f2aaada
	v_cvt_f32_i32_e32 v8, v18
	v_sub_f32_e32 v9, v12, v9
	v_sub_f32_e32 v7, v7, v9
	v_mul_f32_e32 v9, v12, v14
	v_pk_mul_f32 v[14:15], v[8:9], v[162:163]
	v_ldexp_f32 v13, v12, 1
	v_fma_f32 v12, v8, s22, -v14
	v_fmac_f32_e32 v12, 0xb102e308, v8
	v_pk_add_f32 v[8:9], v[14:15], v[12:13]
	v_ldexp_f32 v7, v7, 1
	v_sub_f32_e32 v13, v9, v13
	v_sub_f32_e32 v13, v15, v13
	v_add_f32_e32 v17, v7, v13
	v_mov_b32_e32 v16, v14
	v_pk_add_f32 v[14:15], v[8:9], v[14:15] neg_lo:[0,1] neg_hi:[0,1]
	v_pk_add_f32 v[18:19], v[8:9], v[16:17]
	v_mov_b32_e32 v13, v8
	v_mov_b32_e32 v15, v19
	v_pk_add_f32 v[20:21], v[12:13], v[14:15] neg_lo:[0,1] neg_hi:[0,1]
	v_pk_add_f32 v[12:13], v[12:13], v[14:15]
	v_mov_b32_e32 v16, v17
	v_pk_add_f32 v[14:15], v[12:13], v[8:9] op_sel:[1,0] op_sel_hi:[0,1] neg_lo:[0,1] neg_hi:[0,1]
	v_pk_add_f32 v[22:23], v[18:19], v[14:15] op_sel_hi:[1,0] neg_lo:[0,1] neg_hi:[0,1]
	v_mov_b32_e32 v18, v19
	v_mov_b32_e32 v19, v13
	v_pk_mov_b32 v[14:15], v[8:9], v[14:15] op_sel:[1,0]
	v_mov_b32_e32 v17, v8
	v_pk_add_f32 v[14:15], v[18:19], v[14:15] neg_lo:[0,1] neg_hi:[0,1]
	v_mov_b32_e32 v22, v20
	v_pk_add_f32 v[8:9], v[16:17], v[14:15] neg_lo:[0,1] neg_hi:[0,1]
	v_mov_b32_e32 v21, v13
	v_pk_add_f32 v[14:15], v[22:23], v[8:9]
	s_mov_b32 s22, 0x7f800000
	v_pk_add_f32 v[16:17], v[14:15], v[14:15] op_sel:[0,1] op_sel_hi:[1,0]
	v_cmp_neq_f32_e32 vcc, s22, v6
	v_pk_add_f32 v[12:13], v[12:13], v[16:17] op_sel:[1,0] op_sel_hi:[0,1]
	v_mov_b32_e32 v15, v12
	v_pk_add_f32 v[18:19], v[14:15], v[20:21] neg_lo:[0,1] neg_hi:[0,1]
	v_mov_b32_e32 v9, v16
	v_sub_f32_e32 v7, v14, v18
	v_pk_add_f32 v[8:9], v[8:9], v[18:19] neg_lo:[0,1] neg_hi:[0,1]
	v_sub_f32_e32 v7, v20, v7
	v_add_f32_e32 v7, v8, v7
	v_add_f32_e32 v7, v7, v9
	v_add_f32_e32 v7, v12, v7
	v_cndmask_b32_e32 v7, v209, v7, vcc
	v_cmp_ngt_f32_e32 vcc, -1.0, v6
	s_mov_b32 s22, 0x33800000
	s_nop 0
	v_cndmask_b32_e32 v7, v210, v7, vcc
	v_cmp_neq_f32_e32 vcc, -1.0, v6
	s_nop 1
	v_cndmask_b32_e32 v7, v208, v7, vcc
	v_cmp_lt_f32_e64 vcc, |v6|, s22
	s_nop 1
	v_cndmask_b32_e32 v6, v7, v6, vcc
	v_sub_f32_e32 v4, v4, v6
; __device__ __forceinline__ float bf2f(u16 b) { return __uint_as_float(((unsigned)b) << 16); }
; __device__ __forceinline__ void item_fox(const Params& p, int l, int bl, int h, int qb, LAS unsigned char* lds) {
;     ...
;     { const float bf = p.fox_b_f[l * 4 + h]; float v[8], tot = 0.f;
; #pragma unroll
;       for (int i = 0; i < 8; ++i) { const int s = tid * 8 + i; float ls = 0.f;
;           if (s < nk) { const float xx = bf2f(prow[(size_t)s * NP + C_DF + h]) + bf; ls = fminf(xx, 0.f) - log1pf(__expf(-fabsf(xx))); }
;           tot += ls; v[i] = tot; }
.LBB0_979:
	s_or_b64 exec, exec, s[20:21]
	v_or_b32_e32 v8, 4, v11
	v_cmp_gt_i32_e32 vcc, s25, v8
	v_mov_b32_e32 v7, 0
	v_mov_b32_e32 v6, 0
	s_and_saveexec_b64 s[20:21], vcc
	s_cbranch_execz .LBB0_981
	v_mov_b64_e32 v[12:13], s[0:1]
	v_mad_i64_i32 v[8:9], s[28:29], v8, s33, v[12:13]
	s_lshl_b32 s30, s23, 1
	v_lshl_add_u64 v[8:9], v[8:9], 0, s[30:31]
	v_add_co_u32_e32 v8, vcc, 0x1000, v8
	s_mov_b32 s22, 0xbfb8aa3b
	s_nop 0
	v_addc_co_u32_e32 v9, vcc, 0, v9, vcc
	s_waitcnt vmcnt(3)
	v_mov_b32_e32 v6, v216
	v_lshlrev_b32_e32 v6, 16, v6
	v_add_f32_e32 v8, v0, v6
	v_min_f32_e32 v6, 0, v8
	v_mul_f32_e64 v8, |v8|, s22
	v_exp_f32_e32 v8, v8
	s_mov_b32 s22, 0x3f2aaaab
	v_add_f32_e32 v9, 1.0, v8
	v_add_f32_e32 v12, -1.0, v9
	v_sub_f32_e32 v13, v12, v9
	v_add_f32_e32 v13, 1.0, v13
	v_sub_f32_e32 v12, v8, v12
	v_add_f32_e32 v14, v12, v13
	v_frexp_mant_f32_e32 v12, v9
	v_cmp_gt_f32_e32 vcc, s22, v12
	v_cvt_f64_f32_e32 v[12:13], v9
	v_frexp_exp_i32_f64_e32 v12, v[12:13]
	v_subbrev_co_u32_e32 v20, vcc, 0, v12, vcc
	v_sub_u32_e32 v12, 0, v20
	v_ldexp_f32 v9, v9, v12
	v_ldexp_f32 v12, v14, v12
	v_add_f32_e32 v14, -1.0, v9
	v_add_f32_e32 v13, 1.0, v14
	v_sub_f32_e32 v13, v9, v13
	v_add_f32_e32 v15, v12, v13
	v_add_f32_e32 v13, 1.0, v9
	v_add_f32_e32 v16, -1.0, v13
	v_sub_f32_e32 v9, v9, v16
	v_add_f32_e32 v9, v12, v9
	v_add_f32_e32 v21, v13, v9
	v_rcp_f32_e32 v22, v21
	v_sub_f32_e32 v12, v21, v13
	v_add_f32_e32 v13, v14, v15
	v_sub_f32_e32 v9, v9, v12
	v_mul_f32_e32 v24, v13, v22
	v_sub_f32_e32 v12, v13, v14
	v_mul_f32_e32 v14, v21, v24
	v_fma_f32 v16, v24, v21, -v14
	v_fmac_f32_e32 v16, v24, v9
	v_sub_f32_e32 v23, v15, v12
	v_add_f32_e32 v12, v14, v16
	v_sub_f32_e32 v15, v13, v12
	v_pk_add_f32 v[18:19], v[12:13], v[14:15] neg_lo:[0,1] neg_hi:[0,1]
	v_mov_b32_e32 v17, v12
	v_pk_add_f32 v[12:13], v[18:19], v[16:17] neg_lo:[0,1] neg_hi:[0,1]
	s_mov_b32 s22, 0x3f317218
	v_add_f32_e32 v13, v23, v13
	v_add_f32_e32 v12, v12, v13
	v_add_f32_e32 v13, v15, v12
	v_mul_f32_e32 v23, v22, v13
	v_mul_f32_e32 v14, v21, v23
	v_fma_f32 v16, v23, v21, -v14
	v_fmac_f32_e32 v16, v23, v9
	v_sub_f32_e32 v9, v15, v13
	v_add_f32_e32 v9, v12, v9
	v_add_f32_e32 v12, v14, v16
	v_sub_f32_e32 v15, v13, v12
	v_pk_add_f32 v[18:19], v[12:13], v[14:15] neg_lo:[0,1] neg_hi:[0,1]
	v_mov_b32_e32 v17, v12
	v_pk_add_f32 v[12:13], v[18:19], v[16:17] neg_lo:[0,1] neg_hi:[0,1]
	s_nop 0
	v_add_f32_e32 v9, v9, v13
	v_add_f32_e32 v9, v12, v9
	v_add_f32_e32 v13, v24, v23
	v_add_f32_e32 v9, v15, v9
	v_sub_f32_e32 v12, v13, v24
	v_mul_f32_e32 v9, v22, v9
	v_sub_f32_e32 v12, v23, v12
	v_add_f32_e32 v9, v12, v9
	v_add_f32_e32 v14, v13, v9
	v_mul_f32_e32 v16, v14, v14
	v_fmamk_f32 v12, v16, 0x3e9b6dac, v201
	v_fmaak_f32 v163, v16, v12, 0x3f2aaada
	v_cvt_f32_i32_e32 v12, v20
	v_sub_f32_e32 v13, v14, v13
	v_sub_f32_e32 v9, v9, v13
	v_mul_f32_e32 v13, v14, v16
	v_pk_mul_f32 v[16:17], v[12:13], v[162:163]
	v_ldexp_f32 v15, v14, 1
	v_fma_f32 v14, v12, s22, -v16
	v_fmac_f32_e32 v14, 0xb102e308, v12
	v_pk_add_f32 v[12:13], v[16:17], v[14:15]
	v_ldexp_f32 v9, v9, 1
	v_sub_f32_e32 v15, v13, v15
	v_sub_f32_e32 v15, v17, v15
	v_add_f32_e32 v19, v9, v15
	v_mov_b32_e32 v18, v16
	v_pk_add_f32 v[16:17], v[12:13], v[16:17] neg_lo:[0,1] neg_hi:[0,1]
	v_pk_add_f32 v[20:21], v[12:13], v[18:19]
	v_mov_b32_e32 v15, v12
	v_mov_b32_e32 v17, v21
	v_pk_add_f32 v[22:23], v[14:15], v[16:17] neg_lo:[0,1] neg_hi:[0,1]
	v_pk_add_f32 v[14:15], v[14:15], v[16:17]
	v_mov_b32_e32 v18, v19
	v_pk_add_f32 v[16:17], v[14:15], v[12:13] op_sel:[1,0] op_sel_hi:[0,1] neg_lo:[0,1] neg_hi:[0,1]
	v_pk_add_f32 v[24:25], v[20:21], v[16:17] op_sel_hi:[1,0] neg_lo:[0,1] neg_hi:[0,1]
	v_mov_b32_e32 v20, v21
	v_mov_b32_e32 v21, v15
	v_pk_mov_b32 v[16:17], v[12:13], v[16:17] op_sel:[1,0]
	v_mov_b32_e32 v19, v12
	v_pk_add_f32 v[16:17], v[20:21], v[16:17] neg_lo:[0,1] neg_hi:[0,1]
	v_mov_b32_e32 v24, v22
	v_pk_add_f32 v[12:13], v[18:19], v[16:17] neg_lo:[0,1] neg_hi:[0,1]
	v_mov_b32_e32 v23, v15
	v_pk_add_f32 v[16:17], v[24:25], v[12:13]
	s_mov_b32 s22, 0x7f800000
	v_pk_add_f32 v[18:19], v[16:17], v[16:17] op_sel:[0,1] op_sel_hi:[1,0]
	v_cmp_neq_f32_e32 vcc, s22, v8
	v_pk_add_f32 v[14:15], v[14:15], v[18:19] op_sel:[1,0] op_sel_hi:[0,1]
	v_mov_b32_e32 v17, v14
	v_pk_add_f32 v[20:21], v[16:17], v[22:23] neg_lo:[0,1] neg_hi:[0,1]
	v_mov_b32_e32 v13, v18
	v_sub_f32_e32 v9, v16, v20
	v_pk_add_f32 v[12:13], v[12:13], v[20:21] neg_lo:[0,1] neg_hi:[0,1]
	v_sub_f32_e32 v9, v22, v9
	v_add_f32_e32 v9, v12, v9
	v_add_f32_e32 v9, v9, v13
	v_add_f32_e32 v9, v14, v9
	v_cndmask_b32_e32 v9, v209, v9, vcc
	v_cmp_ngt_f32_e32 vcc, -1.0, v8
	s_mov_b32 s22, 0x33800000
	s_nop 0
	v_cndmask_b32_e32 v9, v210, v9, vcc
	v_cmp_neq_f32_e32 vcc, -1.0, v8
	s_nop 1
	v_cndmask_b32_e32 v9, v208, v9, vcc
	v_cmp_lt_f32_e64 vcc, |v8|, s22
	s_nop 1
	v_cndmask_b32_e32 v8, v9, v8, vcc
	v_sub_f32_e32 v6, v6, v8
; __device__ __forceinline__ float bf2f(u16 b) { return __uint_as_float(((unsigned)b) << 16); }
; __device__ __forceinline__ void item_fox(const Params& p, int l, int bl, int h, int qb, LAS unsigned char* lds) {
;     ...
;     { const float bf = p.fox_b_f[l * 4 + h]; float v[8], tot = 0.f;
; #pragma unroll
;       for (int i = 0; i < 8; ++i) { const int s = tid * 8 + i; float ls = 0.f;
;           if (s < nk) { const float xx = bf2f(prow[(size_t)s * NP + C_DF + h]) + bf; ls = fminf(xx, 0.f) - log1pf(__expf(-fabsf(xx))); }
;           tot += ls; v[i] = tot; }
.LBB0_981:
	s_or_b64 exec, exec, s[20:21]
	v_or_b32_e32 v8, 5, v11
	v_cmp_gt_i32_e32 vcc, s25, v8
	s_and_saveexec_b64 s[20:21], vcc
	s_cbranch_execz .LBB0_983
	v_mov_b64_e32 v[12:13], s[0:1]
	v_mad_i64_i32 v[8:9], s[28:29], v8, s33, v[12:13]
	s_lshl_b32 s30, s23, 1
	v_lshl_add_u64 v[8:9], v[8:9], 0, s[30:31]
	v_add_co_u32_e32 v8, vcc, 0x1000, v8
	s_mov_b32 s22, 0xbfb8aa3b
	s_nop 0
	v_addc_co_u32_e32 v9, vcc, 0, v9, vcc
	s_waitcnt vmcnt(2)
	v_mov_b32_e32 v7, v217
	v_lshlrev_b32_e32 v7, 16, v7
	v_add_f32_e32 v8, v0, v7
	v_min_f32_e32 v7, 0, v8
	v_mul_f32_e64 v8, |v8|, s22
	v_exp_f32_e32 v8, v8
	s_mov_b32 s22, 0x3f2aaaab
	v_add_f32_e32 v9, 1.0, v8
	v_add_f32_e32 v12, -1.0, v9
	v_sub_f32_e32 v13, v12, v9
	v_add_f32_e32 v13, 1.0, v13
	v_sub_f32_e32 v12, v8, v12
	v_add_f32_e32 v14, v12, v13
	v_frexp_mant_f32_e32 v12, v9
	v_cmp_gt_f32_e32 vcc, s22, v12
	v_cvt_f64_f32_e32 v[12:13], v9
	v_frexp_exp_i32_f64_e32 v12, v[12:13]
	v_subbrev_co_u32_e32 v20, vcc, 0, v12, vcc
	v_sub_u32_e32 v12, 0, v20
	v_ldexp_f32 v9, v9, v12
	v_ldexp_f32 v12, v14, v12
	v_add_f32_e32 v14, -1.0, v9
	v_add_f32_e32 v13, 1.0, v14
	v_sub_f32_e32 v13, v9, v13
	v_add_f32_e32 v15, v12, v13
	v_add_f32_e32 v13, 1.0, v9
	v_add_f32_e32 v16, -1.0, v13
	v_sub_f32_e32 v9, v9, v16
	v_add_f32_e32 v9, v12, v9
	v_add_f32_e32 v21, v13, v9
	v_rcp_f32_e32 v22, v21
	v_sub_f32_e32 v12, v21, v13
	v_add_f32_e32 v13, v14, v15
	v_sub_f32_e32 v9, v9, v12
	v_mul_f32_e32 v24, v13, v22
	v_sub_f32_e32 v12, v13, v14
	v_mul_f32_e32 v14, v21, v24
	v_fma_f32 v16, v24, v21, -v14
	v_fmac_f32_e32 v16, v24, v9
	v_sub_f32_e32 v23, v15, v12
	v_add_f32_e32 v12, v14, v16
	v_sub_f32_e32 v15, v13, v12
	v_pk_add_f32 v[18:19], v[12:13], v[14:15] neg_lo:[0,1] neg_hi:[0,1]
	v_mov_b32_e32 v17, v12
	v_pk_add_f32 v[12:13], v[18:19], v[16:17] neg_lo:[0,1] neg_hi:[0,1]
	s_mov_b32 s22, 0x3f317218
	v_add_f32_e32 v13, v23, v13
	v_add_f32_e32 v12, v12, v13
	v_add_f32_e32 v13, v15, v12
	v_mul_f32_e32 v23, v22, v13
	v_mul_f32_e32 v14, v21, v23
	v_fma_f32 v16, v23, v21, -v14
	v_fmac_f32_e32 v16, v23, v9
	v_sub_f32_e32 v9, v15, v13
	v_add_f32_e32 v9, v12, v9
	v_add_f32_e32 v12, v14, v16
	v_sub_f32_e32 v15, v13, v12
	v_pk_add_f32 v[18:19], v[12:13], v[14:15] neg_lo:[0,1] neg_hi:[0,1]
	v_mov_b32_e32 v17, v12
	v_pk_add_f32 v[12:13], v[18:19], v[16:17] neg_lo:[0,1] neg_hi:[0,1]
	s_nop 0
	v_add_f32_e32 v9, v9, v13
	v_add_f32_e32 v9, v12, v9
	v_add_f32_e32 v13, v24, v23
	v_add_f32_e32 v9, v15, v9
	v_sub_f32_e32 v12, v13, v24
	v_mul_f32_e32 v9, v22, v9
	v_sub_f32_e32 v12, v23, v12
	v_add_f32_e32 v9, v12, v9
	v_add_f32_e32 v14, v13, v9
	v_mul_f32_e32 v16, v14, v14
	v_fmamk_f32 v12, v16, 0x3e9b6dac, v201
	v_fmaak_f32 v163, v16, v12, 0x3f2aaada
	v_cvt_f32_i32_e32 v12, v20
	v_sub_f32_e32 v13, v14, v13
	v_sub_f32_e32 v9, v9, v13
	v_mul_f32_e32 v13, v14, v16
	v_pk_mul_f32 v[16:17], v[12:13], v[162:163]
	v_ldexp_f32 v15, v14, 1
	v_fma_f32 v14, v12, s22, -v16
	v_fmac_f32_e32 v14, 0xb102e308, v12
	v_pk_add_f32 v[12:13], v[16:17], v[14:15]
	v_ldexp_f32 v9, v9, 1
	v_sub_f32_e32 v15, v13, v15
	v_sub_f32_e32 v15, v17, v15
	v_add_f32_e32 v19, v9, v15
	v_mov_b32_e32 v18, v16
	v_pk_add_f32 v[16:17], v[12:13], v[16:17] neg_lo:[0,1] neg_hi:[0,1]
	v_pk_add_f32 v[20:21], v[12:13], v[18:19]
	v_mov_b32_e32 v15, v12
	v_mov_b32_e32 v17, v21
	v_pk_add_f32 v[22:23], v[14:15], v[16:17] neg_lo:[0,1] neg_hi:[0,1]
	v_pk_add_f32 v[14:15], v[14:15], v[16:17]
	v_mov_b32_e32 v18, v19
	v_pk_add_f32 v[16:17], v[14:15], v[12:13] op_sel:[1,0] op_sel_hi:[0,1] neg_lo:[0,1] neg_hi:[0,1]
	v_pk_add_f32 v[24:25], v[20:21], v[16:17] op_sel_hi:[1,0] neg_lo:[0,1] neg_hi:[0,1]
	v_mov_b32_e32 v20, v21
	v_mov_b32_e32 v21, v15
	v_pk_mov_b32 v[16:17], v[12:13], v[16:17] op_sel:[1,0]
	v_mov_b32_e32 v19, v12
	v_pk_add_f32 v[16:17], v[20:21], v[16:17] neg_lo:[0,1] neg_hi:[0,1]
	v_mov_b32_e32 v24, v22
	v_pk_add_f32 v[12:13], v[18:19], v[16:17] neg_lo:[0,1] neg_hi:[0,1]
	v_mov_b32_e32 v23, v15
	v_pk_add_f32 v[16:17], v[24:25], v[12:13]
	s_mov_b32 s22, 0x7f800000
	v_pk_add_f32 v[18:19], v[16:17], v[16:17] op_sel:[0,1] op_sel_hi:[1,0]
	v_cmp_neq_f32_e32 vcc, s22, v8
	v_pk_add_f32 v[14:15], v[14:15], v[18:19] op_sel:[1,0] op_sel_hi:[0,1]
	v_mov_b32_e32 v17, v14
	v_pk_add_f32 v[20:21], v[16:17], v[22:23] neg_lo:[0,1] neg_hi:[0,1]
	v_mov_b32_e32 v13, v18
	v_sub_f32_e32 v9, v16, v20
	v_pk_add_f32 v[12:13], v[12:13], v[20:21] neg_lo:[0,1] neg_hi:[0,1]
	v_sub_f32_e32 v9, v22, v9
	v_add_f32_e32 v9, v12, v9
	v_add_f32_e32 v9, v9, v13
	v_add_f32_e32 v9, v14, v9
	v_cndmask_b32_e32 v9, v209, v9, vcc
	v_cmp_ngt_f32_e32 vcc, -1.0, v8
	s_mov_b32 s22, 0x33800000
	s_nop 0
	v_cndmask_b32_e32 v9, v210, v9, vcc
	v_cmp_neq_f32_e32 vcc, -1.0, v8
	s_nop 1
	v_cndmask_b32_e32 v9, v208, v9, vcc
	v_cmp_lt_f32_e64 vcc, |v8|, s22
	s_nop 1
	v_cndmask_b32_e32 v8, v9, v8, vcc
	v_sub_f32_e32 v7, v7, v8
; __device__ __forceinline__ float bf2f(u16 b) { return __uint_as_float(((unsigned)b) << 16); }
; __device__ __forceinline__ void item_fox(const Params& p, int l, int bl, int h, int qb, LAS unsigned char* lds) {
;     ...
;     { const float bf = p.fox_b_f[l * 4 + h]; float v[8], tot = 0.f;
; #pragma unroll
;       for (int i = 0; i < 8; ++i) { const int s = tid * 8 + i; float ls = 0.f;
;           if (s < nk) { const float xx = bf2f(prow[(size_t)s * NP + C_DF + h]) + bf; ls = fminf(xx, 0.f) - log1pf(__expf(-fabsf(xx))); }
;           tot += ls; v[i] = tot; }
.LBB0_983:
	s_or_b64 exec, exec, s[20:21]
	v_or_b32_e32 v8, 6, v11
	v_cmp_gt_i32_e32 vcc, s25, v8
	v_mov_b32_e32 v12, 0
	v_mov_b32_e32 v13, 0
	s_and_saveexec_b64 s[20:21], vcc
	s_cbranch_execz .LBB0_985
	v_mov_b64_e32 v[14:15], s[0:1]
	v_mad_i64_i32 v[8:9], s[28:29], v8, s33, v[14:15]
	s_lshl_b32 s30, s23, 1
	v_lshl_add_u64 v[8:9], v[8:9], 0, s[30:31]
	v_add_co_u32_e32 v8, vcc, 0x1000, v8
	s_mov_b32 s22, 0xbfb8aa3b
	s_nop 0
	v_addc_co_u32_e32 v9, vcc, 0, v9, vcc
	s_waitcnt vmcnt(1)
	v_mov_b32_e32 v8, v218
	v_lshlrev_b32_e32 v8, 16, v8
	v_add_f32_e32 v9, v0, v8
	v_min_f32_e32 v8, 0, v9
	v_mul_f32_e64 v9, |v9|, s22
	v_exp_f32_e32 v9, v9
	s_mov_b32 s22, 0x3f2aaaab
	v_add_f32_e32 v13, 1.0, v9
	v_add_f32_e32 v14, -1.0, v13
	v_sub_f32_e32 v15, v14, v13
	v_add_f32_e32 v15, 1.0, v15
	v_sub_f32_e32 v14, v9, v14
	v_add_f32_e32 v16, v14, v15
	v_frexp_mant_f32_e32 v14, v13
	v_cmp_gt_f32_e32 vcc, s22, v14
	v_cvt_f64_f32_e32 v[14:15], v13
	v_frexp_exp_i32_f64_e32 v14, v[14:15]
	v_subbrev_co_u32_e32 v22, vcc, 0, v14, vcc
	v_sub_u32_e32 v14, 0, v22
	v_ldexp_f32 v13, v13, v14
	v_ldexp_f32 v14, v16, v14
	v_add_f32_e32 v16, -1.0, v13
	v_add_f32_e32 v15, 1.0, v16
	v_sub_f32_e32 v15, v13, v15
	v_add_f32_e32 v17, v14, v15
	v_add_f32_e32 v15, 1.0, v13
	v_add_f32_e32 v18, -1.0, v15
	v_sub_f32_e32 v13, v13, v18
	v_add_f32_e32 v13, v14, v13
	v_add_f32_e32 v23, v15, v13
	v_rcp_f32_e32 v24, v23
	v_sub_f32_e32 v14, v23, v15
	v_add_f32_e32 v15, v16, v17
	v_sub_f32_e32 v13, v13, v14
	v_mul_f32_e32 v26, v15, v24
	v_sub_f32_e32 v14, v15, v16
	v_mul_f32_e32 v16, v23, v26
	v_fma_f32 v18, v26, v23, -v16
	v_fmac_f32_e32 v18, v26, v13
	v_sub_f32_e32 v25, v17, v14
	v_add_f32_e32 v14, v16, v18
	v_sub_f32_e32 v17, v15, v14
	v_pk_add_f32 v[20:21], v[14:15], v[16:17] neg_lo:[0,1] neg_hi:[0,1]
	v_mov_b32_e32 v19, v14
	v_pk_add_f32 v[14:15], v[20:21], v[18:19] neg_lo:[0,1] neg_hi:[0,1]
	s_mov_b32 s22, 0x3f317218
	v_add_f32_e32 v15, v25, v15
	v_add_f32_e32 v14, v14, v15
	v_add_f32_e32 v15, v17, v14
	v_mul_f32_e32 v25, v24, v15
	v_mul_f32_e32 v16, v23, v25
	v_fma_f32 v18, v25, v23, -v16
	v_fmac_f32_e32 v18, v25, v13
	v_sub_f32_e32 v13, v17, v15
	v_add_f32_e32 v13, v14, v13
	v_add_f32_e32 v14, v16, v18
	v_sub_f32_e32 v17, v15, v14
	v_pk_add_f32 v[20:21], v[14:15], v[16:17] neg_lo:[0,1] neg_hi:[0,1]
	v_mov_b32_e32 v19, v14
	v_pk_add_f32 v[14:15], v[20:21], v[18:19] neg_lo:[0,1] neg_hi:[0,1]
	s_nop 0
	v_add_f32_e32 v13, v13, v15
	v_add_f32_e32 v13, v14, v13
	v_add_f32_e32 v15, v26, v25
	v_add_f32_e32 v13, v17, v13
	v_sub_f32_e32 v14, v15, v26
	v_mul_f32_e32 v13, v24, v13
	v_sub_f32_e32 v14, v25, v14
	v_add_f32_e32 v13, v14, v13
	v_add_f32_e32 v16, v15, v13
	v_mul_f32_e32 v18, v16, v16
	v_fmamk_f32 v14, v18, 0x3e9b6dac, v201
	v_fmaak_f32 v163, v18, v14, 0x3f2aaada
	v_cvt_f32_i32_e32 v14, v22
	v_sub_f32_e32 v15, v16, v15
	v_sub_f32_e32 v13, v13, v15
	v_mul_f32_e32 v15, v16, v18
	v_pk_mul_f32 v[18:19], v[14:15], v[162:163]
	v_ldexp_f32 v17, v16, 1
	v_fma_f32 v16, v14, s22, -v18
	v_fmac_f32_e32 v16, 0xb102e308, v14
	v_pk_add_f32 v[14:15], v[18:19], v[16:17]
	v_ldexp_f32 v13, v13, 1
	v_sub_f32_e32 v17, v15, v17
	v_sub_f32_e32 v17, v19, v17
	v_add_f32_e32 v21, v13, v17
	v_mov_b32_e32 v20, v18
	v_pk_add_f32 v[18:19], v[14:15], v[18:19] neg_lo:[0,1] neg_hi:[0,1]
	v_pk_add_f32 v[22:23], v[14:15], v[20:21]
	v_mov_b32_e32 v17, v14
	v_mov_b32_e32 v19, v23
	v_pk_add_f32 v[24:25], v[16:17], v[18:19] neg_lo:[0,1] neg_hi:[0,1]
	v_pk_add_f32 v[16:17], v[16:17], v[18:19]
	v_mov_b32_e32 v20, v21
	v_pk_add_f32 v[18:19], v[16:17], v[14:15] op_sel:[1,0] op_sel_hi:[0,1] neg_lo:[0,1] neg_hi:[0,1]
	v_pk_add_f32 v[26:27], v[22:23], v[18:19] op_sel_hi:[1,0] neg_lo:[0,1] neg_hi:[0,1]
	v_mov_b32_e32 v22, v23
	v_mov_b32_e32 v23, v17
	v_pk_mov_b32 v[18:19], v[14:15], v[18:19] op_sel:[1,0]
	v_mov_b32_e32 v21, v14
	v_pk_add_f32 v[18:19], v[22:23], v[18:19] neg_lo:[0,1] neg_hi:[0,1]
	v_mov_b32_e32 v26, v24
	v_pk_add_f32 v[14:15], v[20:21], v[18:19] neg_lo:[0,1] neg_hi:[0,1]
	v_mov_b32_e32 v25, v17
	v_pk_add_f32 v[18:19], v[26:27], v[14:15]
	s_mov_b32 s22, 0x7f800000
	v_pk_add_f32 v[20:21], v[18:19], v[18:19] op_sel:[0,1] op_sel_hi:[1,0]
	v_cmp_neq_f32_e32 vcc, s22, v9
	v_pk_add_f32 v[16:17], v[16:17], v[20:21] op_sel:[1,0] op_sel_hi:[0,1]
	v_mov_b32_e32 v19, v16
	v_pk_add_f32 v[22:23], v[18:19], v[24:25] neg_lo:[0,1] neg_hi:[0,1]
	v_mov_b32_e32 v15, v20
	v_sub_f32_e32 v13, v18, v22
	v_pk_add_f32 v[14:15], v[14:15], v[22:23] neg_lo:[0,1] neg_hi:[0,1]
	v_sub_f32_e32 v13, v24, v13
	v_add_f32_e32 v13, v14, v13
	v_add_f32_e32 v13, v13, v15
	v_add_f32_e32 v13, v16, v13
	v_cndmask_b32_e32 v13, v209, v13, vcc
	v_cmp_ngt_f32_e32 vcc, -1.0, v9
	s_mov_b32 s22, 0x33800000
	s_nop 0
	v_cndmask_b32_e32 v13, v210, v13, vcc
	v_cmp_neq_f32_e32 vcc, -1.0, v9
	s_nop 1
	v_cndmask_b32_e32 v13, v208, v13, vcc
	v_cmp_lt_f32_e64 vcc, |v9|, s22
	s_nop 1
	v_cndmask_b32_e32 v9, v13, v9, vcc
	v_sub_f32_e32 v13, v8, v9
; __device__ __forceinline__ float bf2f(u16 b) { return __uint_as_float(((unsigned)b) << 16); }
; __device__ __forceinline__ void item_fox(const Params& p, int l, int bl, int h, int qb, LAS unsigned char* lds) {
;     ...
;     { const float bf = p.fox_b_f[l * 4 + h]; float v[8], tot = 0.f;
; #pragma unroll
;       for (int i = 0; i < 8; ++i) { const int s = tid * 8 + i; float ls = 0.f;
;           if (s < nk) { const float xx = bf2f(prow[(size_t)s * NP + C_DF + h]) + bf; ls = fminf(xx, 0.f) - log1pf(__expf(-fabsf(xx))); }
;           tot += ls; v[i] = tot; }
.LBB0_985:
	s_or_b64 exec, exec, s[20:21]
	v_or_b32_e32 v8, 7, v11
	v_cmp_gt_i32_e32 vcc, s25, v8
	s_and_saveexec_b64 s[20:21], vcc
	s_cbranch_execz .LBB0_987
	v_mov_b64_e32 v[14:15], s[0:1]
	v_mad_i64_i32 v[8:9], s[28:29], v8, s33, v[14:15]
	s_lshl_b32 s30, s23, 1
	v_lshl_add_u64 v[8:9], v[8:9], 0, s[30:31]
	v_add_co_u32_e32 v8, vcc, 0x1000, v8
	s_mov_b32 s22, 0xbfb8aa3b
	s_nop 0
	v_addc_co_u32_e32 v9, vcc, 0, v9, vcc
	s_waitcnt vmcnt(0)
	v_mov_b32_e32 v8, v219
	v_lshlrev_b32_e32 v8, 16, v8
	v_add_f32_e32 v8, v0, v8
	v_min_f32_e32 v0, 0, v8
	v_mul_f32_e64 v8, |v8|, s22
	v_exp_f32_e32 v8, v8
	s_mov_b32 s22, 0x3f2aaaab
	v_add_f32_e32 v9, 1.0, v8
	v_add_f32_e32 v12, -1.0, v9
	v_sub_f32_e32 v14, v12, v9
	v_add_f32_e32 v14, 1.0, v14
	v_sub_f32_e32 v12, v8, v12
	v_add_f32_e32 v12, v12, v14
	v_frexp_mant_f32_e32 v14, v9
	v_cmp_gt_f32_e32 vcc, s22, v14
	v_cvt_f64_f32_e32 v[14:15], v9
	v_frexp_exp_i32_f64_e32 v14, v[14:15]
	v_subbrev_co_u32_e32 v22, vcc, 0, v14, vcc
	v_sub_u32_e32 v14, 0, v22
	v_ldexp_f32 v9, v9, v14
	v_ldexp_f32 v12, v12, v14
	v_add_f32_e32 v14, -1.0, v9
	v_add_f32_e32 v15, 1.0, v14
	v_sub_f32_e32 v15, v9, v15
	v_add_f32_e32 v16, v12, v15
	v_add_f32_e32 v15, 1.0, v9
	v_add_f32_e32 v17, -1.0, v15
	v_sub_f32_e32 v9, v9, v17
	v_add_f32_e32 v9, v12, v9
	v_add_f32_e32 v12, v15, v9
	v_rcp_f32_e32 v23, v12
	v_sub_f32_e32 v15, v12, v15
	v_sub_f32_e32 v9, v9, v15
	v_add_f32_e32 v15, v14, v16
	v_sub_f32_e32 v14, v15, v14
	v_mul_f32_e32 v25, v15, v23
	v_sub_f32_e32 v24, v16, v14
	v_mul_f32_e32 v16, v12, v25
	v_fma_f32 v18, v25, v12, -v16
	v_fmac_f32_e32 v18, v25, v9
	v_add_f32_e32 v14, v16, v18
	v_sub_f32_e32 v17, v15, v14
	v_pk_add_f32 v[20:21], v[14:15], v[16:17] neg_lo:[0,1] neg_hi:[0,1]
	v_mov_b32_e32 v19, v14
	v_pk_add_f32 v[14:15], v[20:21], v[18:19] neg_lo:[0,1] neg_hi:[0,1]
	s_mov_b32 s22, 0x3f317218
	v_add_f32_e32 v15, v24, v15
	v_add_f32_e32 v14, v14, v15
	v_add_f32_e32 v15, v17, v14
	v_mul_f32_e32 v24, v23, v15
	v_mul_f32_e32 v16, v12, v24
	v_fma_f32 v18, v24, v12, -v16
	v_fmac_f32_e32 v18, v24, v9
	v_sub_f32_e32 v9, v17, v15
	v_add_f32_e32 v9, v14, v9
	v_add_f32_e32 v14, v16, v18
	v_sub_f32_e32 v17, v15, v14
	v_pk_add_f32 v[20:21], v[14:15], v[16:17] neg_lo:[0,1] neg_hi:[0,1]
	v_mov_b32_e32 v19, v14
	v_pk_add_f32 v[14:15], v[20:21], v[18:19] neg_lo:[0,1] neg_hi:[0,1]
	v_add_f32_e32 v12, v25, v24
	v_add_f32_e32 v9, v9, v15
	v_add_f32_e32 v9, v14, v9
	v_add_f32_e32 v9, v17, v9
	v_sub_f32_e32 v14, v12, v25
	v_mul_f32_e32 v9, v23, v9
	v_sub_f32_e32 v14, v24, v14
	v_add_f32_e32 v9, v14, v9
	v_add_f32_e32 v15, v12, v9
	v_mul_f32_e32 v16, v15, v15
	v_fmamk_f32 v14, v16, 0x3e9b6dac, v201
	v_fmaak_f32 v163, v16, v14, 0x3f2aaada
	v_cvt_f32_i32_e32 v14, v22
	v_sub_f32_e32 v12, v15, v12
	v_ldexp_f32 v17, v15, 1
	v_mul_f32_e32 v15, v15, v16
	v_pk_mul_f32 v[18:19], v[14:15], v[162:163]
	v_sub_f32_e32 v9, v9, v12
	v_fma_f32 v16, v14, s22, -v18
	v_fmac_f32_e32 v16, 0xb102e308, v14
	v_pk_add_f32 v[14:15], v[18:19], v[16:17]
	v_ldexp_f32 v9, v9, 1
	v_sub_f32_e32 v12, v15, v17
	v_sub_f32_e32 v12, v19, v12
	v_add_f32_e32 v21, v9, v12
	v_mov_b32_e32 v20, v18
	v_pk_add_f32 v[18:19], v[14:15], v[18:19] neg_lo:[0,1] neg_hi:[0,1]
	v_pk_add_f32 v[22:23], v[14:15], v[20:21]
	v_mov_b32_e32 v17, v14
	v_mov_b32_e32 v19, v23
	v_pk_add_f32 v[24:25], v[16:17], v[18:19] neg_lo:[0,1] neg_hi:[0,1]
	v_pk_add_f32 v[16:17], v[16:17], v[18:19]
	v_mov_b32_e32 v20, v21
	v_pk_add_f32 v[18:19], v[16:17], v[14:15] op_sel:[1,0] op_sel_hi:[0,1] neg_lo:[0,1] neg_hi:[0,1]
	v_pk_add_f32 v[26:27], v[22:23], v[18:19] op_sel_hi:[1,0] neg_lo:[0,1] neg_hi:[0,1]
	v_mov_b32_e32 v22, v23
	v_mov_b32_e32 v23, v17
	v_pk_mov_b32 v[18:19], v[14:15], v[18:19] op_sel:[1,0]
	v_mov_b32_e32 v21, v14
	v_pk_add_f32 v[18:19], v[22:23], v[18:19] neg_lo:[0,1] neg_hi:[0,1]
	v_mov_b32_e32 v26, v24
	v_pk_add_f32 v[14:15], v[20:21], v[18:19] neg_lo:[0,1] neg_hi:[0,1]
	v_mov_b32_e32 v25, v17
	v_pk_add_f32 v[18:19], v[26:27], v[14:15]
	s_mov_b32 s22, 0x7f800000
	v_pk_add_f32 v[20:21], v[18:19], v[18:19] op_sel:[0,1] op_sel_hi:[1,0]
	v_cmp_neq_f32_e32 vcc, s22, v8
	v_pk_add_f32 v[16:17], v[16:17], v[20:21] op_sel:[1,0] op_sel_hi:[0,1]
	v_mov_b32_e32 v19, v16
	v_pk_add_f32 v[22:23], v[18:19], v[24:25] neg_lo:[0,1] neg_hi:[0,1]
	v_mov_b32_e32 v15, v20
	v_sub_f32_e32 v9, v18, v22
	v_pk_add_f32 v[14:15], v[14:15], v[22:23] neg_lo:[0,1] neg_hi:[0,1]
	v_sub_f32_e32 v9, v24, v9
	v_add_f32_e32 v9, v14, v9
	v_add_f32_e32 v9, v9, v15
	v_add_f32_e32 v9, v16, v9
	v_cndmask_b32_e32 v9, v209, v9, vcc
	v_cmp_ngt_f32_e32 vcc, -1.0, v8
	s_mov_b32 s22, 0x33800000
	s_nop 0
	v_cndmask_b32_e32 v9, v210, v9, vcc
	v_cmp_neq_f32_e32 vcc, -1.0, v8
	s_nop 1
	v_cndmask_b32_e32 v9, v208, v9, vcc
	v_cmp_lt_f32_e64 vcc, |v8|, s22
	s_nop 1
	v_cndmask_b32_e32 v8, v9, v8, vcc
	v_sub_f32_e32 v12, v0, v8
